# RWKV scan: per-step LDS operand reads issued one step ahead into a second register set (steps 1-13), in-step waits removed
# baseline (speedup 1.0000x reference)
.LBB0_595:
	s_andn2_saveexec_b64 s[0:1], s[20:21]
	s_cbranch_execz .LBB0_609
	s_bitcmp1_b32 s25, 0
	s_cselect_b32 s20, 0x6000, 0
	v_add_u32_e32 v1, s20, v143
	ds_read_b128 v[32:35], v1
	ds_read_b128 v[40:43], v1 offset:16
	s_and_b32 s20, s25, 1
	s_mul_i32 s21, s20, 0x6000
	s_add_i32 s21, s21, 0
	s_waitcnt lgkmcnt(1)
	v_pk_mul_f32 v[2:3], v[66:67], v[34:35] op_sel_hi:[1,0]
	v_pk_mul_f32 v[34:35], v[64:65], v[34:35] op_sel:[0,1]
	v_pk_fma_f32 v[2:3], v[70:71], v[32:33], v[2:3] op_sel_hi:[1,0,1]
	v_pk_fma_f32 v[32:33], v[68:69], v[32:33], v[34:35] op_sel:[0,1,0]
	s_waitcnt lgkmcnt(0)
	v_pk_fma_f32 v[2:3], v[62:63], v[40:41], v[2:3] op_sel_hi:[1,0,1]
	v_pk_fma_f32 v[32:33], v[60:61], v[40:41], v[32:33] op_sel:[0,1,0]
	v_pk_fma_f32 v[2:3], v[46:47], v[42:43], v[2:3] op_sel_hi:[1,0,1]
	v_pk_fma_f32 v[32:33], v[44:45], v[42:43], v[32:33] op_sel:[0,1,0]
	v_lshl_add_u32 v152, v97, 2, s21
	v_pk_add_f32 v[2:3], v[2:3], v[32:33]
	v_lshl_add_u32 v151, v98, 2, s21
	ds_read_b128 v[72:75], v152 offset:4096
	ds_read_b128 v[154:157], v152 offset:4112
	ds_read_b128 v[158:161], v152 offset:8192
	ds_read_b128 v[166:169], v152 offset:8208
	ds_read_b128 v[170:173], v152 offset:12288
	ds_read_b128 v[174:177], v152 offset:12304
	ds_read_b128 v[178:181], v152 offset:16384
	ds_read_b128 v[198:201], v152 offset:16400
	ds_read_b64 v[202:203], v151 offset:20480
	ds_read_b128 v[36:39], v1 offset:256
	ds_read_b128 v[28:31], v1 offset:272
	v_add_f32_dpp v2, v2, v2 quad_perm:[1,0,3,2] row_mask:0xf bank_mask:0xf bound_ctrl:1
	v_add_f32_dpp v3, v3, v3 quad_perm:[1,0,3,2] row_mask:0xf bank_mask:0xf bound_ctrl:1
	s_lshl_b32 s20, s20, 12
	v_add_u32_e32 v153, s20, v99
	v_add_f32_dpp v2, v2, v2 quad_perm:[2,3,0,1] row_mask:0xf bank_mask:0xf bound_ctrl:1
	v_add_f32_dpp v3, v3, v3 quad_perm:[2,3,0,1] row_mask:0xf bank_mask:0xf bound_ctrl:1
	s_nop 0
	v_add_f32_dpp v32, v2, v2 row_half_mirror row_mask:0xf bank_mask:0xf bound_ctrl:1
	v_add_f32_dpp v33, v3, v3 row_half_mirror row_mask:0xf bank_mask:0xf bound_ctrl:1
	s_waitcnt lgkmcnt(8)
	v_pk_mul_f32 v[2:3], v[158:159], v[32:33] op_sel_hi:[0,1]
	s_waitcnt lgkmcnt(2)
	ds_read_b128 v[208:211], v152 offset:4352
	ds_read_b128 v[212:215], v152 offset:4368
	ds_read_b128 v[216:219], v152 offset:8448
	ds_read_b128 v[220:223], v152 offset:8464
	ds_read_b128 v[224:227], v152 offset:12544
	ds_read_b128 v[228:231], v152 offset:12560
	ds_read_b128 v[232:235], v152 offset:16640
	ds_read_b128 v[236:239], v152 offset:16656
	ds_read_b64 v[240:241], v151 offset:20736
	v_pk_fma_f32 v[2:3], v[170:171], v[202:203], v[2:3] op_sel_hi:[0,1,1] neg_lo:[0,0,1] neg_hi:[0,0,1]
	v_pk_mul_f32 v[34:35], v[158:159], v[32:33] op_sel:[1,0]
	v_pk_fma_f32 v[2:3], v[70:71], v[72:73], v[2:3] op_sel_hi:[1,0,1]
	v_pk_fma_f32 v[34:35], v[170:171], v[202:203], v[34:35] op_sel:[1,0,0] neg_lo:[0,0,1] neg_hi:[0,0,1]
	v_pk_mul_f32 v[42:43], v[160:161], v[32:33] op_sel_hi:[0,1]
	v_pk_fma_f32 v[68:69], v[68:69], v[72:73], v[34:35] op_sel:[0,1,0]
	v_pk_fma_f32 v[42:43], v[172:173], v[202:203], v[42:43] op_sel_hi:[0,1,1] neg_lo:[0,0,1] neg_hi:[0,0,1]
	v_pk_mul_f32 v[70:71], v[160:161], v[32:33] op_sel:[1,0]
	v_pk_fma_f32 v[66:67], v[66:67], v[74:75], v[42:43] op_sel_hi:[1,0,1]
	v_pk_fma_f32 v[70:71], v[172:173], v[202:203], v[70:71] op_sel:[1,0,0] neg_lo:[0,0,1] neg_hi:[0,0,1]
	v_pk_fma_f32 v[40:41], v[178:179], v[68:69], 0 op_sel:[1,0,0] op_sel_hi:[1,1,0]
	v_pk_fma_f32 v[64:65], v[64:65], v[74:75], v[70:71] op_sel:[0,1,0]
	v_pk_fma_f32 v[40:41], v[180:181], v[64:65], v[40:41] op_sel:[1,0,0]
	v_pk_mul_f32 v[42:43], v[166:167], v[32:33] op_sel_hi:[0,1]
	v_pk_fma_f32 v[42:43], v[174:175], v[202:203], v[42:43] op_sel_hi:[0,1,1] neg_lo:[0,0,1] neg_hi:[0,0,1]
	v_pk_fma_f32 v[62:63], v[62:63], v[154:155], v[42:43] op_sel_hi:[1,0,1]
	v_pk_mul_f32 v[42:43], v[166:167], v[32:33] op_sel:[1,0]
	v_pk_fma_f32 v[34:35], v[178:179], v[2:3], 0 op_sel_hi:[0,1,0]
	v_pk_fma_f32 v[42:43], v[174:175], v[202:203], v[42:43] op_sel:[1,0,0] neg_lo:[0,0,1] neg_hi:[0,0,1]
	v_pk_fma_f32 v[60:61], v[60:61], v[154:155], v[42:43] op_sel:[0,1,0]
	v_pk_mul_f32 v[42:43], v[168:169], v[32:33] op_sel_hi:[0,1]
	v_pk_fma_f32 v[34:35], v[180:181], v[66:67], v[34:35] op_sel_hi:[0,1,1]
	v_pk_fma_f32 v[42:43], v[176:177], v[202:203], v[42:43] op_sel_hi:[0,1,1] neg_lo:[0,0,1] neg_hi:[0,0,1]
	v_pk_mul_f32 v[32:33], v[168:169], v[32:33] op_sel:[1,0]
	v_pk_fma_f32 v[34:35], v[198:199], v[62:63], v[34:35] op_sel_hi:[0,1,1]
	v_pk_fma_f32 v[46:47], v[46:47], v[156:157], v[42:43] op_sel_hi:[1,0,1]
	v_pk_fma_f32 v[32:33], v[176:177], v[202:203], v[32:33] op_sel:[1,0,0] neg_lo:[0,0,1] neg_hi:[0,0,1]
	v_pk_fma_f32 v[40:41], v[198:199], v[60:61], v[40:41] op_sel:[1,0,0]
	v_pk_fma_f32 v[44:45], v[44:45], v[156:157], v[32:33] op_sel:[0,1,0]
	v_pk_fma_f32 v[32:33], v[200:201], v[46:47], v[34:35] op_sel_hi:[0,1,1]
	v_pk_fma_f32 v[34:35], v[200:201], v[44:45], v[40:41] op_sel:[1,0,0]
	v_pk_add_f32 v[32:33], v[32:33], v[34:35]
	s_nop 1
	v_add_f32_dpp v32, v32, v32 quad_perm:[1,0,3,2] row_mask:0xf bank_mask:0xf bound_ctrl:1
	v_add_f32_dpp v33, v33, v33 quad_perm:[1,0,3,2] row_mask:0xf bank_mask:0xf bound_ctrl:1
	s_nop 0
	v_add_f32_dpp v32, v32, v32 quad_perm:[2,3,0,1] row_mask:0xf bank_mask:0xf bound_ctrl:1
	v_add_f32_dpp v33, v33, v33 quad_perm:[2,3,0,1] row_mask:0xf bank_mask:0xf bound_ctrl:1
	s_nop 0
	v_add_f32_dpp v32, v32, v32 row_half_mirror row_mask:0xf bank_mask:0xf bound_ctrl:1
	v_add_f32_dpp v33, v33, v33 row_half_mirror row_mask:0xf bank_mask:0xf bound_ctrl:1
	s_and_saveexec_b64 s[20:21], s[14:15]
	ds_write_b64 v153, v[32:33] offset:49152
	s_or_b64 exec, exec, s[20:21]
	s_waitcnt lgkmcnt(1)
	v_pk_mul_f32 v[202:203], v[38:39], v[66:67] op_sel_hi:[0,1]
	v_pk_fma_f32 v[202:203], v[36:37], v[2:3], v[202:203] op_sel_hi:[0,1,1]
	v_pk_mul_f32 v[38:39], v[38:39], v[64:65] op_sel:[1,0]
	v_pk_fma_f32 v[36:37], v[36:37], v[68:69], v[38:39] op_sel:[1,0,0]
	s_waitcnt lgkmcnt(0)
	v_pk_fma_f32 v[38:39], v[28:29], v[62:63], v[202:203] op_sel_hi:[0,1,1]
	v_pk_fma_f32 v[28:29], v[28:29], v[60:61], v[36:37] op_sel:[1,0,0]
	v_pk_fma_f32 v[36:37], v[30:31], v[46:47], v[38:39] op_sel_hi:[0,1,1]
	v_pk_fma_f32 v[28:29], v[30:31], v[44:45], v[28:29] op_sel:[1,0,0]
	v_pk_add_f32 v[28:29], v[36:37], v[28:29]
	ds_read_b128 v[100:103], v152 offset:4608
	ds_read_b128 v[104:107], v152 offset:4624
	ds_read_b128 v[108:111], v152 offset:8704
	ds_read_b128 v[112:115], v152 offset:8720
	ds_read_b128 v[116:119], v152 offset:12800
	ds_read_b128 v[120:123], v152 offset:12816
	ds_read_b128 v[124:127], v152 offset:16896
	ds_read_b128 v[128:131], v152 offset:16912
	ds_read_b64 v[132:133], v151 offset:20992
	ds_read_b128 v[40:43], v1 offset:512
	ds_read_b128 v[32:35], v1 offset:528
	v_add_f32_dpp v28, v28, v28 quad_perm:[1,0,3,2] row_mask:0xf bank_mask:0xf bound_ctrl:1
	v_add_f32_dpp v29, v29, v29 quad_perm:[1,0,3,2] row_mask:0xf bank_mask:0xf bound_ctrl:1
	s_nop 0
	v_add_f32_dpp v28, v28, v28 quad_perm:[2,3,0,1] row_mask:0xf bank_mask:0xf bound_ctrl:1
	v_add_f32_dpp v29, v29, v29 quad_perm:[2,3,0,1] row_mask:0xf bank_mask:0xf bound_ctrl:1
	s_nop 0
	v_add_f32_dpp v28, v28, v28 row_half_mirror row_mask:0xf bank_mask:0xf bound_ctrl:1
	v_add_f32_dpp v29, v29, v29 row_half_mirror row_mask:0xf bank_mask:0xf bound_ctrl:1
	v_pk_mul_f32 v[30:31], v[216:217], v[28:29] op_sel_hi:[0,1]
	v_pk_fma_f32 v[30:31], v[224:225], v[240:241], v[30:31] op_sel_hi:[0,1,1] neg_lo:[0,0,1] neg_hi:[0,0,1]
	v_pk_fma_f32 v[2:3], v[2:3], v[208:209], v[30:31] op_sel_hi:[1,0,1]
	v_pk_mul_f32 v[30:31], v[216:217], v[28:29] op_sel:[1,0]
	v_pk_mul_f32 v[38:39], v[218:219], v[28:29] op_sel_hi:[0,1]
	v_pk_fma_f32 v[30:31], v[224:225], v[240:241], v[30:31] op_sel:[1,0,0] neg_lo:[0,0,1] neg_hi:[0,0,1]
	v_pk_fma_f32 v[38:39], v[226:227], v[240:241], v[38:39] op_sel_hi:[0,1,1] neg_lo:[0,0,1] neg_hi:[0,0,1]
	v_pk_fma_f32 v[68:69], v[68:69], v[208:209], v[30:31] op_sel:[0,1,0]
	v_pk_fma_f32 v[66:67], v[66:67], v[210:211], v[38:39] op_sel_hi:[1,0,1]
	v_pk_mul_f32 v[70:71], v[218:219], v[28:29] op_sel:[1,0]
	v_pk_fma_f32 v[70:71], v[226:227], v[240:241], v[70:71] op_sel:[1,0,0] neg_lo:[0,0,1] neg_hi:[0,0,1]
	v_pk_fma_f32 v[36:37], v[232:233], v[68:69], 0 op_sel:[1,0,0] op_sel_hi:[1,1,0]
	v_pk_fma_f32 v[64:65], v[64:65], v[210:211], v[70:71] op_sel:[0,1,0]
	v_pk_fma_f32 v[36:37], v[234:235], v[64:65], v[36:37] op_sel:[1,0,0]
	v_pk_mul_f32 v[38:39], v[220:221], v[28:29] op_sel_hi:[0,1]
	v_pk_fma_f32 v[38:39], v[228:229], v[240:241], v[38:39] op_sel_hi:[0,1,1] neg_lo:[0,0,1] neg_hi:[0,0,1]
	v_pk_fma_f32 v[62:63], v[62:63], v[212:213], v[38:39] op_sel_hi:[1,0,1]
	v_pk_mul_f32 v[38:39], v[220:221], v[28:29] op_sel:[1,0]
	v_pk_fma_f32 v[30:31], v[232:233], v[2:3], 0 op_sel_hi:[0,1,0]
	v_pk_fma_f32 v[38:39], v[228:229], v[240:241], v[38:39] op_sel:[1,0,0] neg_lo:[0,0,1] neg_hi:[0,0,1]
	v_pk_fma_f32 v[60:61], v[60:61], v[212:213], v[38:39] op_sel:[0,1,0]
	v_pk_mul_f32 v[38:39], v[222:223], v[28:29] op_sel_hi:[0,1]
	v_pk_fma_f32 v[30:31], v[234:235], v[66:67], v[30:31] op_sel_hi:[0,1,1]
	v_pk_fma_f32 v[38:39], v[230:231], v[240:241], v[38:39] op_sel_hi:[0,1,1] neg_lo:[0,0,1] neg_hi:[0,0,1]
	v_pk_mul_f32 v[28:29], v[222:223], v[28:29] op_sel:[1,0]
	v_pk_fma_f32 v[30:31], v[236:237], v[62:63], v[30:31] op_sel_hi:[0,1,1]
	v_pk_fma_f32 v[46:47], v[46:47], v[214:215], v[38:39] op_sel_hi:[1,0,1]
	v_pk_fma_f32 v[28:29], v[230:231], v[240:241], v[28:29] op_sel:[1,0,0] neg_lo:[0,0,1] neg_hi:[0,0,1]
	v_pk_fma_f32 v[36:37], v[236:237], v[60:61], v[36:37] op_sel:[1,0,0]
	v_pk_fma_f32 v[44:45], v[44:45], v[214:215], v[28:29] op_sel:[0,1,0]
	v_pk_fma_f32 v[28:29], v[238:239], v[46:47], v[30:31] op_sel_hi:[0,1,1]
	v_pk_fma_f32 v[30:31], v[238:239], v[44:45], v[36:37] op_sel:[1,0,0]
	v_pk_add_f32 v[28:29], v[28:29], v[30:31]
	s_nop 1
	v_add_f32_dpp v28, v28, v28 quad_perm:[1,0,3,2] row_mask:0xf bank_mask:0xf bound_ctrl:1
	v_add_f32_dpp v29, v29, v29 quad_perm:[1,0,3,2] row_mask:0xf bank_mask:0xf bound_ctrl:1
	s_nop 0
	v_add_f32_dpp v28, v28, v28 quad_perm:[2,3,0,1] row_mask:0xf bank_mask:0xf bound_ctrl:1
	v_add_f32_dpp v29, v29, v29 quad_perm:[2,3,0,1] row_mask:0xf bank_mask:0xf bound_ctrl:1
	s_nop 0
	v_add_f32_dpp v28, v28, v28 row_half_mirror row_mask:0xf bank_mask:0xf bound_ctrl:1
	v_add_f32_dpp v29, v29, v29 row_half_mirror row_mask:0xf bank_mask:0xf bound_ctrl:1
	s_and_saveexec_b64 s[20:21], s[14:15]
	ds_write_b64 v153, v[28:29] offset:49408
	s_or_b64 exec, exec, s[20:21]
	s_waitcnt lgkmcnt(1)
	v_pk_mul_f32 v[202:203], v[42:43], v[66:67] op_sel_hi:[0,1]
	v_pk_fma_f32 v[202:203], v[40:41], v[2:3], v[202:203] op_sel_hi:[0,1,1]
	v_pk_mul_f32 v[42:43], v[42:43], v[64:65] op_sel:[1,0]
	v_pk_fma_f32 v[40:41], v[40:41], v[68:69], v[42:43] op_sel:[1,0,0]
	s_waitcnt lgkmcnt(0)
	v_pk_fma_f32 v[42:43], v[32:33], v[62:63], v[202:203] op_sel_hi:[0,1,1]
	v_pk_fma_f32 v[32:33], v[32:33], v[60:61], v[40:41] op_sel:[1,0,0]
	v_pk_fma_f32 v[40:41], v[34:35], v[46:47], v[42:43] op_sel_hi:[0,1,1]
	v_pk_fma_f32 v[32:33], v[34:35], v[44:45], v[32:33] op_sel:[1,0,0]
	v_pk_add_f32 v[32:33], v[40:41], v[32:33]
	ds_read_b128 v[208:211], v152 offset:4864
	ds_read_b128 v[212:215], v152 offset:4880
	ds_read_b128 v[216:219], v152 offset:8960
	ds_read_b128 v[220:223], v152 offset:8976
	ds_read_b128 v[224:227], v152 offset:13056
	ds_read_b128 v[228:231], v152 offset:13072
	ds_read_b128 v[232:235], v152 offset:17152
	ds_read_b128 v[236:239], v152 offset:17168
	ds_read_b64 v[240:241], v151 offset:21248
	ds_read_b128 v[36:39], v1 offset:768
	ds_read_b128 v[28:31], v1 offset:784
	v_add_f32_dpp v32, v32, v32 quad_perm:[1,0,3,2] row_mask:0xf bank_mask:0xf bound_ctrl:1
	v_add_f32_dpp v33, v33, v33 quad_perm:[1,0,3,2] row_mask:0xf bank_mask:0xf bound_ctrl:1
	s_nop 0
	v_add_f32_dpp v32, v32, v32 quad_perm:[2,3,0,1] row_mask:0xf bank_mask:0xf bound_ctrl:1
	v_add_f32_dpp v33, v33, v33 quad_perm:[2,3,0,1] row_mask:0xf bank_mask:0xf bound_ctrl:1
	s_nop 0
	v_add_f32_dpp v32, v32, v32 row_half_mirror row_mask:0xf bank_mask:0xf bound_ctrl:1
	v_add_f32_dpp v33, v33, v33 row_half_mirror row_mask:0xf bank_mask:0xf bound_ctrl:1
	v_pk_mul_f32 v[34:35], v[108:109], v[32:33] op_sel_hi:[0,1]
	v_pk_fma_f32 v[34:35], v[116:117], v[132:133], v[34:35] op_sel_hi:[0,1,1] neg_lo:[0,0,1] neg_hi:[0,0,1]
	v_pk_fma_f32 v[2:3], v[2:3], v[100:101], v[34:35] op_sel_hi:[1,0,1]
	v_pk_mul_f32 v[34:35], v[108:109], v[32:33] op_sel:[1,0]
	v_pk_mul_f32 v[42:43], v[110:111], v[32:33] op_sel_hi:[0,1]
	v_pk_fma_f32 v[34:35], v[116:117], v[132:133], v[34:35] op_sel:[1,0,0] neg_lo:[0,0,1] neg_hi:[0,0,1]
	v_pk_fma_f32 v[42:43], v[118:119], v[132:133], v[42:43] op_sel_hi:[0,1,1] neg_lo:[0,0,1] neg_hi:[0,0,1]
	v_pk_fma_f32 v[68:69], v[68:69], v[100:101], v[34:35] op_sel:[0,1,0]
	v_pk_fma_f32 v[66:67], v[66:67], v[102:103], v[42:43] op_sel_hi:[1,0,1]
	v_pk_mul_f32 v[70:71], v[110:111], v[32:33] op_sel:[1,0]
	v_pk_fma_f32 v[70:71], v[118:119], v[132:133], v[70:71] op_sel:[1,0,0] neg_lo:[0,0,1] neg_hi:[0,0,1]
	v_pk_fma_f32 v[40:41], v[124:125], v[68:69], 0 op_sel:[1,0,0] op_sel_hi:[1,1,0]
	v_pk_fma_f32 v[64:65], v[64:65], v[102:103], v[70:71] op_sel:[0,1,0]
	v_pk_fma_f32 v[40:41], v[126:127], v[64:65], v[40:41] op_sel:[1,0,0]
	v_pk_mul_f32 v[42:43], v[112:113], v[32:33] op_sel_hi:[0,1]
	v_pk_fma_f32 v[42:43], v[120:121], v[132:133], v[42:43] op_sel_hi:[0,1,1] neg_lo:[0,0,1] neg_hi:[0,0,1]
	v_pk_fma_f32 v[62:63], v[62:63], v[104:105], v[42:43] op_sel_hi:[1,0,1]
	v_pk_mul_f32 v[42:43], v[112:113], v[32:33] op_sel:[1,0]
	v_pk_fma_f32 v[34:35], v[124:125], v[2:3], 0 op_sel_hi:[0,1,0]
	v_pk_fma_f32 v[42:43], v[120:121], v[132:133], v[42:43] op_sel:[1,0,0] neg_lo:[0,0,1] neg_hi:[0,0,1]
	v_pk_fma_f32 v[60:61], v[60:61], v[104:105], v[42:43] op_sel:[0,1,0]
	v_pk_mul_f32 v[42:43], v[114:115], v[32:33] op_sel_hi:[0,1]
	v_pk_fma_f32 v[34:35], v[126:127], v[66:67], v[34:35] op_sel_hi:[0,1,1]
	v_pk_fma_f32 v[42:43], v[122:123], v[132:133], v[42:43] op_sel_hi:[0,1,1] neg_lo:[0,0,1] neg_hi:[0,0,1]
	v_pk_mul_f32 v[32:33], v[114:115], v[32:33] op_sel:[1,0]
	v_pk_fma_f32 v[34:35], v[128:129], v[62:63], v[34:35] op_sel_hi:[0,1,1]
	v_pk_fma_f32 v[46:47], v[46:47], v[106:107], v[42:43] op_sel_hi:[1,0,1]
	v_pk_fma_f32 v[32:33], v[122:123], v[132:133], v[32:33] op_sel:[1,0,0] neg_lo:[0,0,1] neg_hi:[0,0,1]
	v_pk_fma_f32 v[40:41], v[128:129], v[60:61], v[40:41] op_sel:[1,0,0]
	v_pk_fma_f32 v[44:45], v[44:45], v[106:107], v[32:33] op_sel:[0,1,0]
	v_pk_fma_f32 v[32:33], v[130:131], v[46:47], v[34:35] op_sel_hi:[0,1,1]
	v_pk_fma_f32 v[34:35], v[130:131], v[44:45], v[40:41] op_sel:[1,0,0]
	v_pk_add_f32 v[32:33], v[32:33], v[34:35]
	s_nop 1
	v_add_f32_dpp v32, v32, v32 quad_perm:[1,0,3,2] row_mask:0xf bank_mask:0xf bound_ctrl:1
	v_add_f32_dpp v33, v33, v33 quad_perm:[1,0,3,2] row_mask:0xf bank_mask:0xf bound_ctrl:1
	s_nop 0
	v_add_f32_dpp v32, v32, v32 quad_perm:[2,3,0,1] row_mask:0xf bank_mask:0xf bound_ctrl:1
	v_add_f32_dpp v33, v33, v33 quad_perm:[2,3,0,1] row_mask:0xf bank_mask:0xf bound_ctrl:1
	s_nop 0
	v_add_f32_dpp v32, v32, v32 row_half_mirror row_mask:0xf bank_mask:0xf bound_ctrl:1
	v_add_f32_dpp v33, v33, v33 row_half_mirror row_mask:0xf bank_mask:0xf bound_ctrl:1
	s_and_saveexec_b64 s[20:21], s[14:15]
	ds_write_b64 v153, v[32:33] offset:49664
	s_or_b64 exec, exec, s[20:21]
	s_waitcnt lgkmcnt(1)
	v_pk_mul_f32 v[202:203], v[38:39], v[66:67] op_sel_hi:[0,1]
	v_pk_fma_f32 v[202:203], v[36:37], v[2:3], v[202:203] op_sel_hi:[0,1,1]
	v_pk_mul_f32 v[38:39], v[38:39], v[64:65] op_sel:[1,0]
	v_pk_fma_f32 v[36:37], v[36:37], v[68:69], v[38:39] op_sel:[1,0,0]
	s_waitcnt lgkmcnt(0)
	v_pk_fma_f32 v[38:39], v[28:29], v[62:63], v[202:203] op_sel_hi:[0,1,1]
	v_pk_fma_f32 v[28:29], v[28:29], v[60:61], v[36:37] op_sel:[1,0,0]
	v_pk_fma_f32 v[36:37], v[30:31], v[46:47], v[38:39] op_sel_hi:[0,1,1]
	v_pk_fma_f32 v[28:29], v[30:31], v[44:45], v[28:29] op_sel:[1,0,0]
	v_pk_add_f32 v[28:29], v[36:37], v[28:29]
	ds_read_b128 v[100:103], v152 offset:5120
	ds_read_b128 v[104:107], v152 offset:5136
	ds_read_b128 v[108:111], v152 offset:9216
	ds_read_b128 v[112:115], v152 offset:9232
	ds_read_b128 v[116:119], v152 offset:13312
	ds_read_b128 v[120:123], v152 offset:13328
	ds_read_b128 v[124:127], v152 offset:17408
	ds_read_b128 v[128:131], v152 offset:17424
	ds_read_b64 v[132:133], v151 offset:21504
	ds_read_b128 v[40:43], v1 offset:1024
	ds_read_b128 v[32:35], v1 offset:1040
	v_add_f32_dpp v28, v28, v28 quad_perm:[1,0,3,2] row_mask:0xf bank_mask:0xf bound_ctrl:1
	v_add_f32_dpp v29, v29, v29 quad_perm:[1,0,3,2] row_mask:0xf bank_mask:0xf bound_ctrl:1
	s_nop 0
	v_add_f32_dpp v28, v28, v28 quad_perm:[2,3,0,1] row_mask:0xf bank_mask:0xf bound_ctrl:1
	v_add_f32_dpp v29, v29, v29 quad_perm:[2,3,0,1] row_mask:0xf bank_mask:0xf bound_ctrl:1
	s_nop 0
	v_add_f32_dpp v36, v28, v28 row_half_mirror row_mask:0xf bank_mask:0xf bound_ctrl:1
	v_add_f32_dpp v37, v29, v29 row_half_mirror row_mask:0xf bank_mask:0xf bound_ctrl:1
	v_pk_mul_f32 v[28:29], v[216:217], v[36:37] op_sel_hi:[0,1]
	v_pk_fma_f32 v[28:29], v[224:225], v[240:241], v[28:29] op_sel_hi:[0,1,1] neg_lo:[0,0,1] neg_hi:[0,0,1]
	v_pk_fma_f32 v[2:3], v[2:3], v[208:209], v[28:29] op_sel_hi:[1,0,1]
	v_pk_mul_f32 v[28:29], v[216:217], v[36:37] op_sel:[1,0]
	v_pk_mul_f32 v[30:31], v[218:219], v[36:37] op_sel_hi:[0,1]
	v_pk_fma_f32 v[28:29], v[224:225], v[240:241], v[28:29] op_sel:[1,0,0] neg_lo:[0,0,1] neg_hi:[0,0,1]
	v_pk_fma_f32 v[30:31], v[226:227], v[240:241], v[30:31] op_sel_hi:[0,1,1] neg_lo:[0,0,1] neg_hi:[0,0,1]
	v_pk_fma_f32 v[28:29], v[68:69], v[208:209], v[28:29] op_sel:[0,1,0]
	v_pk_fma_f32 v[30:31], v[66:67], v[210:211], v[30:31] op_sel_hi:[1,0,1]
	v_pk_mul_f32 v[70:71], v[218:219], v[36:37] op_sel:[1,0]
	v_pk_fma_f32 v[70:71], v[226:227], v[240:241], v[70:71] op_sel:[1,0,0] neg_lo:[0,0,1] neg_hi:[0,0,1]
	v_pk_fma_f32 v[68:69], v[232:233], v[28:29], 0 op_sel:[1,0,0] op_sel_hi:[1,1,0]
	v_pk_fma_f32 v[64:65], v[64:65], v[210:211], v[70:71] op_sel:[0,1,0]
	v_pk_fma_f32 v[66:67], v[234:235], v[64:65], v[68:69] op_sel:[1,0,0]
	v_pk_mul_f32 v[68:69], v[220:221], v[36:37] op_sel_hi:[0,1]
	v_pk_fma_f32 v[68:69], v[228:229], v[240:241], v[68:69] op_sel_hi:[0,1,1] neg_lo:[0,0,1] neg_hi:[0,0,1]
	v_pk_fma_f32 v[62:63], v[62:63], v[212:213], v[68:69] op_sel_hi:[1,0,1]
	v_pk_mul_f32 v[68:69], v[220:221], v[36:37] op_sel:[1,0]
	v_pk_fma_f32 v[38:39], v[232:233], v[2:3], 0 op_sel_hi:[0,1,0]
	v_pk_fma_f32 v[68:69], v[228:229], v[240:241], v[68:69] op_sel:[1,0,0] neg_lo:[0,0,1] neg_hi:[0,0,1]
	v_pk_fma_f32 v[38:39], v[234:235], v[30:31], v[38:39] op_sel_hi:[0,1,1]
	v_pk_fma_f32 v[60:61], v[60:61], v[212:213], v[68:69] op_sel:[0,1,0]
	v_pk_fma_f32 v[70:71], v[236:237], v[60:61], v[66:67] op_sel:[1,0,0]
	v_pk_mul_f32 v[66:67], v[222:223], v[36:37] op_sel_hi:[0,1]
	v_pk_fma_f32 v[66:67], v[230:231], v[240:241], v[66:67] op_sel_hi:[0,1,1] neg_lo:[0,0,1] neg_hi:[0,0,1]
	v_pk_mul_f32 v[36:37], v[222:223], v[36:37] op_sel:[1,0]
	v_pk_fma_f32 v[38:39], v[236:237], v[62:63], v[38:39] op_sel_hi:[0,1,1]
	v_pk_fma_f32 v[66:67], v[46:47], v[214:215], v[66:67] op_sel_hi:[1,0,1]
	v_pk_fma_f32 v[36:37], v[230:231], v[240:241], v[36:37] op_sel:[1,0,0] neg_lo:[0,0,1] neg_hi:[0,0,1]
	v_pk_fma_f32 v[68:69], v[44:45], v[214:215], v[36:37] op_sel:[0,1,0]
	v_pk_fma_f32 v[36:37], v[238:239], v[66:67], v[38:39] op_sel_hi:[0,1,1]
	v_pk_fma_f32 v[38:39], v[238:239], v[68:69], v[70:71] op_sel:[1,0,0]
	v_pk_add_f32 v[36:37], v[36:37], v[38:39]
	s_nop 1
	v_add_f32_dpp v36, v36, v36 quad_perm:[1,0,3,2] row_mask:0xf bank_mask:0xf bound_ctrl:1
	v_add_f32_dpp v37, v37, v37 quad_perm:[1,0,3,2] row_mask:0xf bank_mask:0xf bound_ctrl:1
	s_nop 0
	v_add_f32_dpp v36, v36, v36 quad_perm:[2,3,0,1] row_mask:0xf bank_mask:0xf bound_ctrl:1
	v_add_f32_dpp v37, v37, v37 quad_perm:[2,3,0,1] row_mask:0xf bank_mask:0xf bound_ctrl:1
	s_nop 0
	v_add_f32_dpp v36, v36, v36 row_half_mirror row_mask:0xf bank_mask:0xf bound_ctrl:1
	v_add_f32_dpp v37, v37, v37 row_half_mirror row_mask:0xf bank_mask:0xf bound_ctrl:1
	s_and_saveexec_b64 s[20:21], s[14:15]
	ds_write_b64 v153, v[36:37] offset:49920
	s_or_b64 exec, exec, s[20:21]
	s_waitcnt lgkmcnt(1)
	v_pk_mul_f32 v[202:203], v[42:43], v[30:31] op_sel_hi:[0,1]
	v_pk_fma_f32 v[202:203], v[40:41], v[2:3], v[202:203] op_sel_hi:[0,1,1]
	v_pk_mul_f32 v[42:43], v[42:43], v[64:65] op_sel:[1,0]
	v_pk_fma_f32 v[40:41], v[40:41], v[28:29], v[42:43] op_sel:[1,0,0]
	s_waitcnt lgkmcnt(0)
	v_pk_fma_f32 v[42:43], v[32:33], v[62:63], v[202:203] op_sel_hi:[0,1,1]
	v_pk_fma_f32 v[32:33], v[32:33], v[60:61], v[40:41] op_sel:[1,0,0]
	v_pk_fma_f32 v[40:41], v[34:35], v[66:67], v[42:43] op_sel_hi:[0,1,1]
	v_pk_fma_f32 v[32:33], v[34:35], v[68:69], v[32:33] op_sel:[1,0,0]
	v_pk_add_f32 v[32:33], v[40:41], v[32:33]
	ds_read_b128 v[208:211], v152 offset:5376
	ds_read_b128 v[212:215], v152 offset:5392
	ds_read_b128 v[216:219], v152 offset:9472
	ds_read_b128 v[220:223], v152 offset:9488
	ds_read_b128 v[224:227], v152 offset:13568
	ds_read_b128 v[228:231], v152 offset:13584
	ds_read_b128 v[232:235], v152 offset:17664
	ds_read_b128 v[236:239], v152 offset:17680
	ds_read_b64 v[240:241], v151 offset:21760
	ds_read_b128 v[44:47], v1 offset:1280
	ds_read_b128 v[36:39], v1 offset:1296
	v_add_f32_dpp v32, v32, v32 quad_perm:[1,0,3,2] row_mask:0xf bank_mask:0xf bound_ctrl:1
	v_add_f32_dpp v33, v33, v33 quad_perm:[1,0,3,2] row_mask:0xf bank_mask:0xf bound_ctrl:1
	s_nop 0
	v_add_f32_dpp v32, v32, v32 quad_perm:[2,3,0,1] row_mask:0xf bank_mask:0xf bound_ctrl:1
	v_add_f32_dpp v33, v33, v33 quad_perm:[2,3,0,1] row_mask:0xf bank_mask:0xf bound_ctrl:1
	s_nop 0
	v_add_f32_dpp v32, v32, v32 row_half_mirror row_mask:0xf bank_mask:0xf bound_ctrl:1
	v_add_f32_dpp v33, v33, v33 row_half_mirror row_mask:0xf bank_mask:0xf bound_ctrl:1
	v_pk_mul_f32 v[34:35], v[108:109], v[32:33] op_sel_hi:[0,1]
	v_pk_fma_f32 v[34:35], v[116:117], v[132:133], v[34:35] op_sel_hi:[0,1,1] neg_lo:[0,0,1] neg_hi:[0,0,1]
	v_pk_fma_f32 v[2:3], v[2:3], v[100:101], v[34:35] op_sel_hi:[1,0,1]
	v_pk_mul_f32 v[34:35], v[108:109], v[32:33] op_sel:[1,0]
	v_pk_mul_f32 v[42:43], v[110:111], v[32:33] op_sel_hi:[0,1]
	v_pk_fma_f32 v[34:35], v[116:117], v[132:133], v[34:35] op_sel:[1,0,0] neg_lo:[0,0,1] neg_hi:[0,0,1]
	v_pk_fma_f32 v[42:43], v[118:119], v[132:133], v[42:43] op_sel_hi:[0,1,1] neg_lo:[0,0,1] neg_hi:[0,0,1]
	v_pk_fma_f32 v[40:41], v[28:29], v[100:101], v[34:35] op_sel:[0,1,0]
	v_pk_fma_f32 v[42:43], v[30:31], v[102:103], v[42:43] op_sel_hi:[1,0,1]
	v_pk_mul_f32 v[70:71], v[110:111], v[32:33] op_sel:[1,0]
	v_pk_fma_f32 v[70:71], v[118:119], v[132:133], v[70:71] op_sel:[1,0,0] neg_lo:[0,0,1] neg_hi:[0,0,1]
	v_pk_fma_f32 v[34:35], v[124:125], v[40:41], 0 op_sel:[1,0,0] op_sel_hi:[1,1,0]
	v_pk_fma_f32 v[64:65], v[64:65], v[102:103], v[70:71] op_sel:[0,1,0]
	v_pk_fma_f32 v[30:31], v[126:127], v[64:65], v[34:35] op_sel:[1,0,0]
	v_pk_mul_f32 v[34:35], v[112:113], v[32:33] op_sel_hi:[0,1]
	v_pk_fma_f32 v[34:35], v[120:121], v[132:133], v[34:35] op_sel_hi:[0,1,1] neg_lo:[0,0,1] neg_hi:[0,0,1]
	v_pk_fma_f32 v[62:63], v[62:63], v[104:105], v[34:35] op_sel_hi:[1,0,1]
	v_pk_mul_f32 v[34:35], v[112:113], v[32:33] op_sel:[1,0]
	v_pk_fma_f32 v[28:29], v[124:125], v[2:3], 0 op_sel_hi:[0,1,0]
	v_pk_fma_f32 v[34:35], v[120:121], v[132:133], v[34:35] op_sel:[1,0,0] neg_lo:[0,0,1] neg_hi:[0,0,1]
	v_pk_fma_f32 v[60:61], v[60:61], v[104:105], v[34:35] op_sel:[0,1,0]
	v_pk_mul_f32 v[34:35], v[114:115], v[32:33] op_sel_hi:[0,1]
	v_pk_fma_f32 v[34:35], v[122:123], v[132:133], v[34:35] op_sel_hi:[0,1,1] neg_lo:[0,0,1] neg_hi:[0,0,1]
	v_pk_fma_f32 v[72:73], v[66:67], v[106:107], v[34:35] op_sel_hi:[1,0,1]
	v_pk_mul_f32 v[32:33], v[114:115], v[32:33] op_sel:[1,0]
	v_pk_fma_f32 v[28:29], v[126:127], v[42:43], v[28:29] op_sel_hi:[0,1,1]
	v_pk_fma_f32 v[32:33], v[122:123], v[132:133], v[32:33] op_sel:[1,0,0] neg_lo:[0,0,1] neg_hi:[0,0,1]
	v_pk_fma_f32 v[28:29], v[128:129], v[62:63], v[28:29] op_sel_hi:[0,1,1]
	v_pk_fma_f32 v[30:31], v[128:129], v[60:61], v[30:31] op_sel:[1,0,0]
	v_pk_fma_f32 v[74:75], v[68:69], v[106:107], v[32:33] op_sel:[0,1,0]
	v_pk_fma_f32 v[28:29], v[130:131], v[72:73], v[28:29] op_sel_hi:[0,1,1]
	v_pk_fma_f32 v[30:31], v[130:131], v[74:75], v[30:31] op_sel:[1,0,0]
	v_pk_add_f32 v[28:29], v[28:29], v[30:31]
	s_nop 1
	v_add_f32_dpp v28, v28, v28 quad_perm:[1,0,3,2] row_mask:0xf bank_mask:0xf bound_ctrl:1
	v_add_f32_dpp v29, v29, v29 quad_perm:[1,0,3,2] row_mask:0xf bank_mask:0xf bound_ctrl:1
	s_nop 0
	v_add_f32_dpp v28, v28, v28 quad_perm:[2,3,0,1] row_mask:0xf bank_mask:0xf bound_ctrl:1
	v_add_f32_dpp v29, v29, v29 quad_perm:[2,3,0,1] row_mask:0xf bank_mask:0xf bound_ctrl:1
	s_nop 0
	v_add_f32_dpp v28, v28, v28 row_half_mirror row_mask:0xf bank_mask:0xf bound_ctrl:1
	v_add_f32_dpp v29, v29, v29 row_half_mirror row_mask:0xf bank_mask:0xf bound_ctrl:1
	s_and_saveexec_b64 s[20:21], s[14:15]
	ds_write_b64 v153, v[28:29] offset:50176
	s_or_b64 exec, exec, s[20:21]
	s_waitcnt lgkmcnt(1)
	v_pk_mul_f32 v[66:67], v[46:47], v[42:43] op_sel_hi:[0,1]
	v_pk_fma_f32 v[66:67], v[44:45], v[2:3], v[66:67] op_sel_hi:[0,1,1]
	v_pk_mul_f32 v[46:47], v[46:47], v[64:65] op_sel:[1,0]
	v_pk_fma_f32 v[44:45], v[44:45], v[40:41], v[46:47] op_sel:[1,0,0]
	s_waitcnt lgkmcnt(0)
	v_pk_fma_f32 v[46:47], v[36:37], v[62:63], v[66:67] op_sel_hi:[0,1,1]
	v_pk_fma_f32 v[36:37], v[36:37], v[60:61], v[44:45] op_sel:[1,0,0]
	v_pk_fma_f32 v[44:45], v[38:39], v[72:73], v[46:47] op_sel_hi:[0,1,1]
	v_pk_fma_f32 v[36:37], v[38:39], v[74:75], v[36:37] op_sel:[1,0,0]
	v_pk_add_f32 v[36:37], v[44:45], v[36:37]
	ds_read_b128 v[100:103], v152 offset:5632
	ds_read_b128 v[104:107], v152 offset:5648
	ds_read_b128 v[108:111], v152 offset:9728
	ds_read_b128 v[112:115], v152 offset:9744
	ds_read_b128 v[116:119], v152 offset:13824
	ds_read_b128 v[120:123], v152 offset:13840
	ds_read_b128 v[124:127], v152 offset:17920
	ds_read_b128 v[128:131], v152 offset:17936
	ds_read_b64 v[132:133], v151 offset:22016
	ds_read_b128 v[32:35], v1 offset:1536
	ds_read_b128 v[28:31], v1 offset:1552
	v_add_f32_dpp v36, v36, v36 quad_perm:[1,0,3,2] row_mask:0xf bank_mask:0xf bound_ctrl:1
	v_add_f32_dpp v37, v37, v37 quad_perm:[1,0,3,2] row_mask:0xf bank_mask:0xf bound_ctrl:1
	s_nop 0
	v_add_f32_dpp v36, v36, v36 quad_perm:[2,3,0,1] row_mask:0xf bank_mask:0xf bound_ctrl:1
	v_add_f32_dpp v37, v37, v37 quad_perm:[2,3,0,1] row_mask:0xf bank_mask:0xf bound_ctrl:1
	s_nop 0
	v_add_f32_dpp v36, v36, v36 row_half_mirror row_mask:0xf bank_mask:0xf bound_ctrl:1
	v_add_f32_dpp v37, v37, v37 row_half_mirror row_mask:0xf bank_mask:0xf bound_ctrl:1
	s_nop 0
	v_pk_mul_f32 v[38:39], v[216:217], v[36:37] op_sel_hi:[0,1]
	v_pk_fma_f32 v[38:39], v[224:225], v[240:241], v[38:39] op_sel_hi:[0,1,1] neg_lo:[0,0,1] neg_hi:[0,0,1]
	v_pk_fma_f32 v[70:71], v[2:3], v[208:209], v[38:39] op_sel_hi:[1,0,1]
	v_pk_mul_f32 v[2:3], v[216:217], v[36:37] op_sel:[1,0]
	s_nop 0
	v_pk_fma_f32 v[2:3], v[224:225], v[240:241], v[2:3] op_sel:[1,0,0] neg_lo:[0,0,1] neg_hi:[0,0,1]
	s_nop 0
	v_pk_fma_f32 v[68:69], v[40:41], v[208:209], v[2:3] op_sel:[0,1,0]
	v_pk_mul_f32 v[40:41], v[218:219], v[36:37] op_sel_hi:[0,1]
	v_pk_fma_f32 v[40:41], v[226:227], v[240:241], v[40:41] op_sel_hi:[0,1,1] neg_lo:[0,0,1] neg_hi:[0,0,1]
	v_pk_fma_f32 v[66:67], v[42:43], v[210:211], v[40:41] op_sel_hi:[1,0,1]
	v_pk_mul_f32 v[42:43], v[218:219], v[36:37] op_sel:[1,0]
	v_pk_fma_f32 v[42:43], v[226:227], v[240:241], v[42:43] op_sel:[1,0,0] neg_lo:[0,0,1] neg_hi:[0,0,1]
	v_pk_fma_f32 v[38:39], v[232:233], v[68:69], 0 op_sel:[1,0,0] op_sel_hi:[1,1,0]
	v_pk_fma_f32 v[64:65], v[64:65], v[210:211], v[42:43] op_sel:[0,1,0]
	v_pk_fma_f32 v[38:39], v[234:235], v[64:65], v[38:39] op_sel:[1,0,0]
	v_pk_mul_f32 v[40:41], v[220:221], v[36:37] op_sel_hi:[0,1]
	v_pk_fma_f32 v[40:41], v[228:229], v[240:241], v[40:41] op_sel_hi:[0,1,1] neg_lo:[0,0,1] neg_hi:[0,0,1]
	v_pk_fma_f32 v[62:63], v[62:63], v[212:213], v[40:41] op_sel_hi:[1,0,1]
	v_pk_mul_f32 v[40:41], v[220:221], v[36:37] op_sel:[1,0]
	v_mov_b32_e32 v42, v223
	v_pk_fma_f32 v[40:41], v[228:229], v[240:241], v[40:41] op_sel:[1,0,0] neg_lo:[0,0,1] neg_hi:[0,0,1]
	v_pk_fma_f32 v[2:3], v[232:233], v[70:71], 0 op_sel_hi:[0,1,0]
	v_pk_fma_f32 v[60:61], v[60:61], v[212:213], v[40:41] op_sel:[0,1,0]
	v_pk_mul_f32 v[40:41], v[222:223], v[36:37] op_sel_hi:[0,1]
	v_pk_fma_f32 v[40:41], v[230:231], v[240:241], v[40:41] op_sel_hi:[0,1,1] neg_lo:[0,0,1] neg_hi:[0,0,1]
	v_pk_mul_f32 v[36:37], v[42:43], v[36:37] op_sel_hi:[0,1]
	v_pk_fma_f32 v[2:3], v[234:235], v[66:67], v[2:3] op_sel_hi:[0,1,1]
	v_pk_fma_f32 v[46:47], v[72:73], v[214:215], v[40:41] op_sel_hi:[1,0,1]
	v_mov_b32_e32 v40, v215
	v_pk_fma_f32 v[36:37], v[230:231], v[240:241], v[36:37] op_sel:[1,0,0] neg_lo:[0,0,1] neg_hi:[0,0,1]
	v_pk_fma_f32 v[2:3], v[236:237], v[62:63], v[2:3] op_sel_hi:[0,1,1]
	v_pk_fma_f32 v[38:39], v[236:237], v[60:61], v[38:39] op_sel:[1,0,0]
	v_pk_fma_f32 v[44:45], v[74:75], v[40:41], v[36:37] op_sel_hi:[1,0,1]
	v_pk_fma_f32 v[2:3], v[238:239], v[46:47], v[2:3] op_sel_hi:[0,1,1]
	v_pk_fma_f32 v[36:37], v[238:239], v[44:45], v[38:39] op_sel:[1,0,0]
	v_pk_add_f32 v[2:3], v[2:3], v[36:37]
	s_nop 1
	v_add_f32_dpp v2, v2, v2 quad_perm:[1,0,3,2] row_mask:0xf bank_mask:0xf bound_ctrl:1
	v_add_f32_dpp v3, v3, v3 quad_perm:[1,0,3,2] row_mask:0xf bank_mask:0xf bound_ctrl:1
	s_nop 0
	v_add_f32_dpp v2, v2, v2 quad_perm:[2,3,0,1] row_mask:0xf bank_mask:0xf bound_ctrl:1
	v_add_f32_dpp v3, v3, v3 quad_perm:[2,3,0,1] row_mask:0xf bank_mask:0xf bound_ctrl:1
	s_nop 0
	v_add_f32_dpp v2, v2, v2 row_half_mirror row_mask:0xf bank_mask:0xf bound_ctrl:1
	v_add_f32_dpp v3, v3, v3 row_half_mirror row_mask:0xf bank_mask:0xf bound_ctrl:1
	s_and_saveexec_b64 s[20:21], s[14:15]
	ds_write_b64 v153, v[2:3] offset:50432
	s_or_b64 exec, exec, s[20:21]

.LBB0_612:
	s_andn2_saveexec_b64 s[0:1], s[0:1]
	s_cbranch_execz .LBB0_624
	v_pk_mul_f32 v[2:3], v[66:67], v[34:35] op_sel_hi:[1,0]
	v_pk_fma_f32 v[2:3], v[70:71], v[32:33], v[2:3] op_sel_hi:[1,0,1]
	v_pk_mul_f32 v[34:35], v[64:65], v[34:35] op_sel:[0,1]
	v_pk_fma_f32 v[2:3], v[62:63], v[28:29], v[2:3] op_sel_hi:[1,0,1]
	v_pk_fma_f32 v[32:33], v[68:69], v[32:33], v[34:35] op_sel:[0,1,0]
	v_pk_fma_f32 v[2:3], v[46:47], v[30:31], v[2:3] op_sel_hi:[1,0,1]
	v_pk_fma_f32 v[28:29], v[60:61], v[28:29], v[32:33] op_sel:[0,1,0]
	v_pk_fma_f32 v[28:29], v[44:45], v[30:31], v[28:29] op_sel:[0,1,0]
	s_and_b32 s20, s25, 1
	v_pk_add_f32 v[2:3], v[2:3], v[28:29]
	s_mul_i32 s21, s20, 0x6000
	s_add_i32 s21, s21, 0
	v_add_f32_dpp v2, v2, v2 quad_perm:[1,0,3,2] row_mask:0xf bank_mask:0xf bound_ctrl:1
	v_add_f32_dpp v3, v3, v3 quad_perm:[1,0,3,2] row_mask:0xf bank_mask:0xf bound_ctrl:1
	s_bitcmp1_b32 s25, 0
	v_lshl_add_u32 v152, v97, 2, s21
	v_mov_b32_dpp v28, v2 quad_perm:[2,3,0,1] row_mask:0xf bank_mask:0xf bound_ctrl:1
	v_mov_b32_dpp v29, v3 quad_perm:[2,3,0,1] row_mask:0xf bank_mask:0xf bound_ctrl:1
	v_lshl_add_u32 v1, v98, 2, s21
	s_cselect_b32 s21, 0x6000, 0
	v_pk_add_f32 v[2:3], v[2:3], v[28:29]
	v_add_u32_e32 v151, s21, v143
	ds_read_b128 v[208:211], v152 offset:5888
	ds_read_b128 v[212:215], v152 offset:5904
	ds_read_b128 v[216:219], v152 offset:9984
	ds_read_b128 v[220:223], v152 offset:10000
	ds_read_b128 v[224:227], v152 offset:14080
	ds_read_b128 v[228:231], v152 offset:14096
	ds_read_b128 v[232:235], v152 offset:18176
	ds_read_b128 v[236:239], v152 offset:18192
	ds_read_b64 v[240:241], v1 offset:22272
	ds_read_b128 v[40:43], v151 offset:1792
	ds_read_b128 v[36:39], v151 offset:1808
	v_add_f32_dpp v28, v2, v2 row_half_mirror row_mask:0xf bank_mask:0xf bound_ctrl:1
	v_add_f32_dpp v29, v3, v3 row_half_mirror row_mask:0xf bank_mask:0xf bound_ctrl:1
	s_lshl_b32 s20, s20, 12
	v_pk_mul_f32 v[2:3], v[108:109], v[28:29] op_sel_hi:[0,1]
	v_pk_fma_f32 v[2:3], v[116:117], v[132:133], v[2:3] op_sel_hi:[0,1,1] neg_lo:[0,0,1] neg_hi:[0,0,1]
	v_pk_mul_f32 v[30:31], v[108:109], v[28:29] op_sel:[1,0]
	v_pk_fma_f32 v[2:3], v[70:71], v[100:101], v[2:3] op_sel_hi:[1,0,1]
	v_pk_fma_f32 v[30:31], v[116:117], v[132:133], v[30:31] op_sel:[1,0,0] neg_lo:[0,0,1] neg_hi:[0,0,1]
	v_pk_mul_f32 v[34:35], v[110:111], v[28:29] op_sel_hi:[0,1]
	v_pk_fma_f32 v[32:33], v[68:69], v[100:101], v[30:31] op_sel:[0,1,0]
	v_pk_fma_f32 v[34:35], v[118:119], v[132:133], v[34:35] op_sel_hi:[0,1,1] neg_lo:[0,0,1] neg_hi:[0,0,1]
	v_pk_mul_f32 v[70:71], v[110:111], v[28:29] op_sel:[1,0]
	v_pk_fma_f32 v[34:35], v[66:67], v[102:103], v[34:35] op_sel_hi:[1,0,1]
	v_pk_fma_f32 v[70:71], v[118:119], v[132:133], v[70:71] op_sel:[1,0,0] neg_lo:[0,0,1] neg_hi:[0,0,1]
	v_pk_fma_f32 v[68:69], v[124:125], v[32:33], 0 op_sel:[1,0,0] op_sel_hi:[1,1,0]
	v_pk_fma_f32 v[64:65], v[64:65], v[102:103], v[70:71] op_sel:[0,1,0]
	v_pk_fma_f32 v[66:67], v[126:127], v[64:65], v[68:69] op_sel:[1,0,0]
	v_pk_mul_f32 v[68:69], v[112:113], v[28:29] op_sel_hi:[0,1]
	v_pk_fma_f32 v[68:69], v[120:121], v[132:133], v[68:69] op_sel_hi:[0,1,1] neg_lo:[0,0,1] neg_hi:[0,0,1]
	v_pk_fma_f32 v[62:63], v[62:63], v[104:105], v[68:69] op_sel_hi:[1,0,1]
	v_pk_mul_f32 v[68:69], v[112:113], v[28:29] op_sel:[1,0]
	v_pk_fma_f32 v[30:31], v[124:125], v[2:3], 0 op_sel_hi:[0,1,0]
	v_pk_fma_f32 v[68:69], v[120:121], v[132:133], v[68:69] op_sel:[1,0,0] neg_lo:[0,0,1] neg_hi:[0,0,1]
	v_pk_fma_f32 v[30:31], v[126:127], v[34:35], v[30:31] op_sel_hi:[0,1,1]
	v_pk_fma_f32 v[60:61], v[60:61], v[104:105], v[68:69] op_sel:[0,1,0]
	v_pk_fma_f32 v[70:71], v[128:129], v[60:61], v[66:67] op_sel:[1,0,0]
	v_pk_mul_f32 v[66:67], v[114:115], v[28:29] op_sel_hi:[0,1]
	v_pk_fma_f32 v[66:67], v[122:123], v[132:133], v[66:67] op_sel_hi:[0,1,1] neg_lo:[0,0,1] neg_hi:[0,0,1]
	v_pk_mul_f32 v[28:29], v[114:115], v[28:29] op_sel:[1,0]
	v_pk_fma_f32 v[30:31], v[128:129], v[62:63], v[30:31] op_sel_hi:[0,1,1]
	v_pk_fma_f32 v[66:67], v[46:47], v[106:107], v[66:67] op_sel_hi:[1,0,1]
	v_pk_fma_f32 v[28:29], v[122:123], v[132:133], v[28:29] op_sel:[1,0,0] neg_lo:[0,0,1] neg_hi:[0,0,1]
	v_pk_fma_f32 v[68:69], v[44:45], v[106:107], v[28:29] op_sel:[0,1,0]
	v_pk_fma_f32 v[28:29], v[130:131], v[66:67], v[30:31] op_sel_hi:[0,1,1]
	v_pk_fma_f32 v[30:31], v[130:131], v[68:69], v[70:71] op_sel:[1,0,0]
	v_pk_add_f32 v[28:29], v[28:29], v[30:31]
	v_add_u32_e32 v153, s20, v99
	s_nop 0
	v_add_f32_dpp v28, v28, v28 quad_perm:[1,0,3,2] row_mask:0xf bank_mask:0xf bound_ctrl:1
	v_add_f32_dpp v29, v29, v29 quad_perm:[1,0,3,2] row_mask:0xf bank_mask:0xf bound_ctrl:1
	s_nop 0
	v_add_f32_dpp v28, v28, v28 quad_perm:[2,3,0,1] row_mask:0xf bank_mask:0xf bound_ctrl:1
	v_add_f32_dpp v29, v29, v29 quad_perm:[2,3,0,1] row_mask:0xf bank_mask:0xf bound_ctrl:1
	s_nop 0
	v_add_f32_dpp v28, v28, v28 row_half_mirror row_mask:0xf bank_mask:0xf bound_ctrl:1
	v_add_f32_dpp v29, v29, v29 row_half_mirror row_mask:0xf bank_mask:0xf bound_ctrl:1
	s_and_saveexec_b64 s[20:21], s[14:15]
	ds_write_b64 v153, v[28:29] offset:50688
	s_or_b64 exec, exec, s[20:21]
	s_waitcnt lgkmcnt(1)
	v_pk_mul_f32 v[202:203], v[42:43], v[34:35] op_sel_hi:[0,1]
	v_pk_fma_f32 v[202:203], v[40:41], v[2:3], v[202:203] op_sel_hi:[0,1,1]
	v_pk_mul_f32 v[42:43], v[42:43], v[64:65] op_sel:[1,0]
	v_pk_fma_f32 v[40:41], v[40:41], v[32:33], v[42:43] op_sel:[1,0,0]
	s_waitcnt lgkmcnt(0)
	v_pk_fma_f32 v[42:43], v[36:37], v[62:63], v[202:203] op_sel_hi:[0,1,1]
	v_pk_fma_f32 v[36:37], v[36:37], v[60:61], v[40:41] op_sel:[1,0,0]
	v_pk_fma_f32 v[40:41], v[38:39], v[66:67], v[42:43] op_sel_hi:[0,1,1]
	v_pk_fma_f32 v[36:37], v[38:39], v[68:69], v[36:37] op_sel:[1,0,0]
	v_pk_add_f32 v[36:37], v[40:41], v[36:37]
	ds_read_b128 v[100:103], v152 offset:6144
	ds_read_b128 v[104:107], v152 offset:6160
	ds_read_b128 v[108:111], v152 offset:10240
	ds_read_b128 v[112:115], v152 offset:10256
	ds_read_b128 v[116:119], v152 offset:14336
	ds_read_b128 v[120:123], v152 offset:14352
	ds_read_b128 v[124:127], v152 offset:18432
	ds_read_b128 v[128:131], v152 offset:18448
	ds_read_b64 v[132:133], v1 offset:22528
	ds_read_b128 v[44:47], v151 offset:2048
	ds_read_b128 v[28:31], v151 offset:2064
	v_add_f32_dpp v36, v36, v36 quad_perm:[1,0,3,2] row_mask:0xf bank_mask:0xf bound_ctrl:1
	v_add_f32_dpp v37, v37, v37 quad_perm:[1,0,3,2] row_mask:0xf bank_mask:0xf bound_ctrl:1
	s_nop 0
	v_add_f32_dpp v36, v36, v36 quad_perm:[2,3,0,1] row_mask:0xf bank_mask:0xf bound_ctrl:1
	v_add_f32_dpp v37, v37, v37 quad_perm:[2,3,0,1] row_mask:0xf bank_mask:0xf bound_ctrl:1
	s_nop 0
	v_add_f32_dpp v40, v36, v36 row_half_mirror row_mask:0xf bank_mask:0xf bound_ctrl:1
	v_add_f32_dpp v41, v37, v37 row_half_mirror row_mask:0xf bank_mask:0xf bound_ctrl:1
	v_pk_mul_f32 v[36:37], v[216:217], v[40:41] op_sel_hi:[0,1]
	v_pk_fma_f32 v[36:37], v[224:225], v[240:241], v[36:37] op_sel_hi:[0,1,1] neg_lo:[0,0,1] neg_hi:[0,0,1]
	v_pk_fma_f32 v[2:3], v[2:3], v[208:209], v[36:37] op_sel_hi:[1,0,1]
	v_pk_mul_f32 v[36:37], v[216:217], v[40:41] op_sel:[1,0]
	v_pk_mul_f32 v[38:39], v[218:219], v[40:41] op_sel_hi:[0,1]
	v_pk_fma_f32 v[36:37], v[224:225], v[240:241], v[36:37] op_sel:[1,0,0] neg_lo:[0,0,1] neg_hi:[0,0,1]
	v_pk_fma_f32 v[38:39], v[226:227], v[240:241], v[38:39] op_sel_hi:[0,1,1] neg_lo:[0,0,1] neg_hi:[0,0,1]
	v_pk_fma_f32 v[36:37], v[32:33], v[208:209], v[36:37] op_sel:[0,1,0]
	v_pk_fma_f32 v[38:39], v[34:35], v[210:211], v[38:39] op_sel_hi:[1,0,1]
	v_pk_mul_f32 v[70:71], v[218:219], v[40:41] op_sel:[1,0]
	v_pk_fma_f32 v[70:71], v[226:227], v[240:241], v[70:71] op_sel:[1,0,0] neg_lo:[0,0,1] neg_hi:[0,0,1]
	v_pk_fma_f32 v[42:43], v[232:233], v[36:37], 0 op_sel:[1,0,0] op_sel_hi:[1,1,0]
	v_pk_fma_f32 v[64:65], v[64:65], v[210:211], v[70:71] op_sel:[0,1,0]
	v_pk_fma_f32 v[34:35], v[234:235], v[64:65], v[42:43] op_sel:[1,0,0]
	v_pk_mul_f32 v[42:43], v[220:221], v[40:41] op_sel_hi:[0,1]
	v_pk_fma_f32 v[42:43], v[228:229], v[240:241], v[42:43] op_sel_hi:[0,1,1] neg_lo:[0,0,1] neg_hi:[0,0,1]
	v_pk_fma_f32 v[62:63], v[62:63], v[212:213], v[42:43] op_sel_hi:[1,0,1]
	v_pk_mul_f32 v[42:43], v[220:221], v[40:41] op_sel:[1,0]
	v_pk_fma_f32 v[42:43], v[228:229], v[240:241], v[42:43] op_sel:[1,0,0] neg_lo:[0,0,1] neg_hi:[0,0,1]
	v_pk_fma_f32 v[32:33], v[232:233], v[2:3], 0 op_sel_hi:[0,1,0]
	v_pk_fma_f32 v[60:61], v[60:61], v[212:213], v[42:43] op_sel:[0,1,0]
	v_pk_mul_f32 v[42:43], v[222:223], v[40:41] op_sel_hi:[0,1]
	v_pk_fma_f32 v[42:43], v[230:231], v[240:241], v[42:43] op_sel_hi:[0,1,1] neg_lo:[0,0,1] neg_hi:[0,0,1]
	v_pk_mul_f32 v[40:41], v[222:223], v[40:41] op_sel:[1,0]
	v_pk_fma_f32 v[32:33], v[234:235], v[38:39], v[32:33] op_sel_hi:[0,1,1]
	v_pk_fma_f32 v[66:67], v[66:67], v[214:215], v[42:43] op_sel_hi:[1,0,1]
	v_pk_fma_f32 v[40:41], v[230:231], v[240:241], v[40:41] op_sel:[1,0,0] neg_lo:[0,0,1] neg_hi:[0,0,1]
	v_pk_fma_f32 v[32:33], v[236:237], v[62:63], v[32:33] op_sel_hi:[0,1,1]
	v_pk_fma_f32 v[34:35], v[236:237], v[60:61], v[34:35] op_sel:[1,0,0]
	v_pk_fma_f32 v[68:69], v[68:69], v[214:215], v[40:41] op_sel:[0,1,0]
	v_pk_fma_f32 v[32:33], v[238:239], v[66:67], v[32:33] op_sel_hi:[0,1,1]
	v_pk_fma_f32 v[34:35], v[238:239], v[68:69], v[34:35] op_sel:[1,0,0]
	v_pk_add_f32 v[32:33], v[32:33], v[34:35]
	s_nop 1
	v_add_f32_dpp v32, v32, v32 quad_perm:[1,0,3,2] row_mask:0xf bank_mask:0xf bound_ctrl:1
	v_add_f32_dpp v33, v33, v33 quad_perm:[1,0,3,2] row_mask:0xf bank_mask:0xf bound_ctrl:1
	s_nop 0
	v_add_f32_dpp v32, v32, v32 quad_perm:[2,3,0,1] row_mask:0xf bank_mask:0xf bound_ctrl:1
	v_add_f32_dpp v33, v33, v33 quad_perm:[2,3,0,1] row_mask:0xf bank_mask:0xf bound_ctrl:1
	s_nop 0
	v_add_f32_dpp v32, v32, v32 row_half_mirror row_mask:0xf bank_mask:0xf bound_ctrl:1
	v_add_f32_dpp v33, v33, v33 row_half_mirror row_mask:0xf bank_mask:0xf bound_ctrl:1
	s_and_saveexec_b64 s[20:21], s[14:15]
	ds_write_b64 v153, v[32:33] offset:50944
	s_or_b64 exec, exec, s[20:21]
	s_waitcnt lgkmcnt(1)
	v_pk_mul_f32 v[202:203], v[46:47], v[38:39] op_sel_hi:[0,1]
	v_pk_fma_f32 v[202:203], v[44:45], v[2:3], v[202:203] op_sel_hi:[0,1,1]
	v_pk_mul_f32 v[46:47], v[46:47], v[64:65] op_sel:[1,0]
	v_pk_fma_f32 v[44:45], v[44:45], v[36:37], v[46:47] op_sel:[1,0,0]
	s_waitcnt lgkmcnt(0)
	v_pk_fma_f32 v[46:47], v[28:29], v[62:63], v[202:203] op_sel_hi:[0,1,1]
	v_pk_fma_f32 v[28:29], v[28:29], v[60:61], v[44:45] op_sel:[1,0,0]
	v_pk_fma_f32 v[44:45], v[30:31], v[66:67], v[46:47] op_sel_hi:[0,1,1]
	v_pk_fma_f32 v[28:29], v[30:31], v[68:69], v[28:29] op_sel:[1,0,0]
	v_pk_add_f32 v[28:29], v[44:45], v[28:29]
	ds_read_b128 v[208:211], v152 offset:6400
	ds_read_b128 v[212:215], v152 offset:6416
	ds_read_b128 v[216:219], v152 offset:10496
	ds_read_b128 v[220:223], v152 offset:10512
	ds_read_b128 v[224:227], v152 offset:14592
	ds_read_b128 v[228:231], v152 offset:14608
	ds_read_b128 v[232:235], v152 offset:18688
	ds_read_b128 v[236:239], v152 offset:18704
	ds_read_b64 v[240:241], v1 offset:22784
	ds_read_b128 v[40:43], v151 offset:2304
	ds_read_b128 v[32:35], v151 offset:2320
	v_add_f32_dpp v28, v28, v28 quad_perm:[1,0,3,2] row_mask:0xf bank_mask:0xf bound_ctrl:1
	v_add_f32_dpp v29, v29, v29 quad_perm:[1,0,3,2] row_mask:0xf bank_mask:0xf bound_ctrl:1
	s_nop 0
	v_add_f32_dpp v28, v28, v28 quad_perm:[2,3,0,1] row_mask:0xf bank_mask:0xf bound_ctrl:1
	v_add_f32_dpp v29, v29, v29 quad_perm:[2,3,0,1] row_mask:0xf bank_mask:0xf bound_ctrl:1
	s_nop 0
	v_add_f32_dpp v44, v28, v28 row_half_mirror row_mask:0xf bank_mask:0xf bound_ctrl:1
	v_add_f32_dpp v45, v29, v29 row_half_mirror row_mask:0xf bank_mask:0xf bound_ctrl:1
	v_pk_mul_f32 v[28:29], v[108:109], v[44:45] op_sel_hi:[0,1]
	v_pk_fma_f32 v[28:29], v[116:117], v[132:133], v[28:29] op_sel_hi:[0,1,1] neg_lo:[0,0,1] neg_hi:[0,0,1]
	v_pk_fma_f32 v[2:3], v[2:3], v[100:101], v[28:29] op_sel_hi:[1,0,1]
	v_pk_mul_f32 v[28:29], v[108:109], v[44:45] op_sel:[1,0]
	v_pk_mul_f32 v[30:31], v[110:111], v[44:45] op_sel_hi:[0,1]
	v_pk_fma_f32 v[28:29], v[116:117], v[132:133], v[28:29] op_sel:[1,0,0] neg_lo:[0,0,1] neg_hi:[0,0,1]
	v_pk_fma_f32 v[30:31], v[118:119], v[132:133], v[30:31] op_sel_hi:[0,1,1] neg_lo:[0,0,1] neg_hi:[0,0,1]
	v_pk_fma_f32 v[28:29], v[36:37], v[100:101], v[28:29] op_sel:[0,1,0]
	v_pk_fma_f32 v[30:31], v[38:39], v[102:103], v[30:31] op_sel_hi:[1,0,1]
	v_pk_mul_f32 v[70:71], v[110:111], v[44:45] op_sel:[1,0]
	v_pk_fma_f32 v[70:71], v[118:119], v[132:133], v[70:71] op_sel:[1,0,0] neg_lo:[0,0,1] neg_hi:[0,0,1]
	v_pk_fma_f32 v[46:47], v[124:125], v[28:29], 0 op_sel:[1,0,0] op_sel_hi:[1,1,0]
	v_pk_fma_f32 v[64:65], v[64:65], v[102:103], v[70:71] op_sel:[0,1,0]
	v_pk_fma_f32 v[38:39], v[126:127], v[64:65], v[46:47] op_sel:[1,0,0]
	v_pk_mul_f32 v[46:47], v[112:113], v[44:45] op_sel_hi:[0,1]
	v_pk_fma_f32 v[46:47], v[120:121], v[132:133], v[46:47] op_sel_hi:[0,1,1] neg_lo:[0,0,1] neg_hi:[0,0,1]
	v_pk_fma_f32 v[62:63], v[62:63], v[104:105], v[46:47] op_sel_hi:[1,0,1]
	v_pk_mul_f32 v[46:47], v[112:113], v[44:45] op_sel:[1,0]
	v_pk_fma_f32 v[46:47], v[120:121], v[132:133], v[46:47] op_sel:[1,0,0] neg_lo:[0,0,1] neg_hi:[0,0,1]
	v_pk_fma_f32 v[36:37], v[124:125], v[2:3], 0 op_sel_hi:[0,1,0]
	v_pk_fma_f32 v[60:61], v[60:61], v[104:105], v[46:47] op_sel:[0,1,0]
	v_pk_mul_f32 v[46:47], v[114:115], v[44:45] op_sel_hi:[0,1]
	v_pk_fma_f32 v[46:47], v[122:123], v[132:133], v[46:47] op_sel_hi:[0,1,1] neg_lo:[0,0,1] neg_hi:[0,0,1]
	v_pk_mul_f32 v[44:45], v[114:115], v[44:45] op_sel:[1,0]
	v_pk_fma_f32 v[36:37], v[126:127], v[30:31], v[36:37] op_sel_hi:[0,1,1]
	v_pk_fma_f32 v[66:67], v[66:67], v[106:107], v[46:47] op_sel_hi:[1,0,1]
	v_pk_fma_f32 v[44:45], v[122:123], v[132:133], v[44:45] op_sel:[1,0,0] neg_lo:[0,0,1] neg_hi:[0,0,1]
	v_pk_fma_f32 v[36:37], v[128:129], v[62:63], v[36:37] op_sel_hi:[0,1,1]
	v_pk_fma_f32 v[38:39], v[128:129], v[60:61], v[38:39] op_sel:[1,0,0]
	v_pk_fma_f32 v[68:69], v[68:69], v[106:107], v[44:45] op_sel:[0,1,0]
	v_pk_fma_f32 v[36:37], v[130:131], v[66:67], v[36:37] op_sel_hi:[0,1,1]
	v_pk_fma_f32 v[38:39], v[130:131], v[68:69], v[38:39] op_sel:[1,0,0]
	v_pk_add_f32 v[36:37], v[36:37], v[38:39]
	s_nop 1
	v_add_f32_dpp v36, v36, v36 quad_perm:[1,0,3,2] row_mask:0xf bank_mask:0xf bound_ctrl:1
	v_add_f32_dpp v37, v37, v37 quad_perm:[1,0,3,2] row_mask:0xf bank_mask:0xf bound_ctrl:1
	s_nop 0
	v_add_f32_dpp v36, v36, v36 quad_perm:[2,3,0,1] row_mask:0xf bank_mask:0xf bound_ctrl:1
	v_add_f32_dpp v37, v37, v37 quad_perm:[2,3,0,1] row_mask:0xf bank_mask:0xf bound_ctrl:1
	s_nop 0
	v_add_f32_dpp v36, v36, v36 row_half_mirror row_mask:0xf bank_mask:0xf bound_ctrl:1
	v_add_f32_dpp v37, v37, v37 row_half_mirror row_mask:0xf bank_mask:0xf bound_ctrl:1
	s_and_saveexec_b64 s[20:21], s[14:15]
	ds_write_b64 v153, v[36:37] offset:51200
	s_or_b64 exec, exec, s[20:21]
	s_waitcnt lgkmcnt(1)
	v_pk_mul_f32 v[202:203], v[42:43], v[30:31] op_sel_hi:[0,1]
	v_pk_fma_f32 v[202:203], v[40:41], v[2:3], v[202:203] op_sel_hi:[0,1,1]
	v_pk_mul_f32 v[42:43], v[42:43], v[64:65] op_sel:[1,0]
	v_pk_fma_f32 v[40:41], v[40:41], v[28:29], v[42:43] op_sel:[1,0,0]
	s_waitcnt lgkmcnt(0)
	v_pk_fma_f32 v[42:43], v[32:33], v[62:63], v[202:203] op_sel_hi:[0,1,1]
	v_pk_fma_f32 v[32:33], v[32:33], v[60:61], v[40:41] op_sel:[1,0,0]
	v_pk_fma_f32 v[40:41], v[34:35], v[66:67], v[42:43] op_sel_hi:[0,1,1]
	v_pk_fma_f32 v[32:33], v[34:35], v[68:69], v[32:33] op_sel:[1,0,0]
	v_pk_add_f32 v[32:33], v[40:41], v[32:33]
	ds_read_b128 v[100:103], v152 offset:6656
	ds_read_b128 v[104:107], v152 offset:6672
	ds_read_b128 v[108:111], v152 offset:10752
	ds_read_b128 v[112:115], v152 offset:10768
	ds_read_b128 v[116:119], v152 offset:14848
	ds_read_b128 v[120:123], v152 offset:14864
	ds_read_b128 v[124:127], v152 offset:18944
	ds_read_b128 v[128:131], v152 offset:18960
	ds_read_b64 v[132:133], v1 offset:23040
	ds_read_b128 v[44:47], v151 offset:2560
	ds_read_b128 v[36:39], v151 offset:2576
	v_add_f32_dpp v32, v32, v32 quad_perm:[1,0,3,2] row_mask:0xf bank_mask:0xf bound_ctrl:1
	v_add_f32_dpp v33, v33, v33 quad_perm:[1,0,3,2] row_mask:0xf bank_mask:0xf bound_ctrl:1
	s_nop 0
	v_add_f32_dpp v32, v32, v32 quad_perm:[2,3,0,1] row_mask:0xf bank_mask:0xf bound_ctrl:1
	v_add_f32_dpp v33, v33, v33 quad_perm:[2,3,0,1] row_mask:0xf bank_mask:0xf bound_ctrl:1
	s_nop 0
	v_add_f32_dpp v32, v32, v32 row_half_mirror row_mask:0xf bank_mask:0xf bound_ctrl:1
	v_add_f32_dpp v33, v33, v33 row_half_mirror row_mask:0xf bank_mask:0xf bound_ctrl:1
	v_pk_mul_f32 v[34:35], v[216:217], v[32:33] op_sel_hi:[0,1]
	v_pk_fma_f32 v[34:35], v[224:225], v[240:241], v[34:35] op_sel_hi:[0,1,1] neg_lo:[0,0,1] neg_hi:[0,0,1]
	v_pk_fma_f32 v[2:3], v[2:3], v[208:209], v[34:35] op_sel_hi:[1,0,1]
	v_pk_mul_f32 v[34:35], v[216:217], v[32:33] op_sel:[1,0]
	v_pk_mul_f32 v[42:43], v[218:219], v[32:33] op_sel_hi:[0,1]
	v_pk_fma_f32 v[34:35], v[224:225], v[240:241], v[34:35] op_sel:[1,0,0] neg_lo:[0,0,1] neg_hi:[0,0,1]
	v_pk_fma_f32 v[42:43], v[226:227], v[240:241], v[42:43] op_sel_hi:[0,1,1] neg_lo:[0,0,1] neg_hi:[0,0,1]
	v_pk_fma_f32 v[40:41], v[28:29], v[208:209], v[34:35] op_sel:[0,1,0]
	v_pk_fma_f32 v[42:43], v[30:31], v[210:211], v[42:43] op_sel_hi:[1,0,1]
	v_pk_mul_f32 v[70:71], v[218:219], v[32:33] op_sel:[1,0]
	v_pk_fma_f32 v[70:71], v[226:227], v[240:241], v[70:71] op_sel:[1,0,0] neg_lo:[0,0,1] neg_hi:[0,0,1]
	v_pk_fma_f32 v[34:35], v[232:233], v[40:41], 0 op_sel:[1,0,0] op_sel_hi:[1,1,0]
	v_pk_fma_f32 v[64:65], v[64:65], v[210:211], v[70:71] op_sel:[0,1,0]
	v_pk_fma_f32 v[30:31], v[234:235], v[64:65], v[34:35] op_sel:[1,0,0]
	v_pk_mul_f32 v[34:35], v[220:221], v[32:33] op_sel_hi:[0,1]
	v_pk_fma_f32 v[34:35], v[228:229], v[240:241], v[34:35] op_sel_hi:[0,1,1] neg_lo:[0,0,1] neg_hi:[0,0,1]
	v_pk_fma_f32 v[62:63], v[62:63], v[212:213], v[34:35] op_sel_hi:[1,0,1]
	v_pk_mul_f32 v[34:35], v[220:221], v[32:33] op_sel:[1,0]
	v_pk_fma_f32 v[28:29], v[232:233], v[2:3], 0 op_sel_hi:[0,1,0]
	v_pk_fma_f32 v[34:35], v[228:229], v[240:241], v[34:35] op_sel:[1,0,0] neg_lo:[0,0,1] neg_hi:[0,0,1]
	v_pk_fma_f32 v[60:61], v[60:61], v[212:213], v[34:35] op_sel:[0,1,0]
	v_pk_mul_f32 v[34:35], v[222:223], v[32:33] op_sel_hi:[0,1]
	v_pk_fma_f32 v[34:35], v[230:231], v[240:241], v[34:35] op_sel_hi:[0,1,1] neg_lo:[0,0,1] neg_hi:[0,0,1]
	v_pk_fma_f32 v[72:73], v[66:67], v[214:215], v[34:35] op_sel_hi:[1,0,1]
	v_pk_mul_f32 v[32:33], v[222:223], v[32:33] op_sel:[1,0]
	v_pk_fma_f32 v[28:29], v[234:235], v[42:43], v[28:29] op_sel_hi:[0,1,1]
	v_pk_fma_f32 v[32:33], v[230:231], v[240:241], v[32:33] op_sel:[1,0,0] neg_lo:[0,0,1] neg_hi:[0,0,1]
	v_pk_fma_f32 v[28:29], v[236:237], v[62:63], v[28:29] op_sel_hi:[0,1,1]
	v_pk_fma_f32 v[30:31], v[236:237], v[60:61], v[30:31] op_sel:[1,0,0]
	v_pk_fma_f32 v[74:75], v[68:69], v[214:215], v[32:33] op_sel:[0,1,0]
	v_pk_fma_f32 v[28:29], v[238:239], v[72:73], v[28:29] op_sel_hi:[0,1,1]
	v_pk_fma_f32 v[30:31], v[238:239], v[74:75], v[30:31] op_sel:[1,0,0]
	v_pk_add_f32 v[28:29], v[28:29], v[30:31]
	s_nop 1
	v_add_f32_dpp v28, v28, v28 quad_perm:[1,0,3,2] row_mask:0xf bank_mask:0xf bound_ctrl:1
	v_add_f32_dpp v29, v29, v29 quad_perm:[1,0,3,2] row_mask:0xf bank_mask:0xf bound_ctrl:1
	s_nop 0
	v_add_f32_dpp v28, v28, v28 quad_perm:[2,3,0,1] row_mask:0xf bank_mask:0xf bound_ctrl:1
	v_add_f32_dpp v29, v29, v29 quad_perm:[2,3,0,1] row_mask:0xf bank_mask:0xf bound_ctrl:1
	s_nop 0
	v_add_f32_dpp v28, v28, v28 row_half_mirror row_mask:0xf bank_mask:0xf bound_ctrl:1
	v_add_f32_dpp v29, v29, v29 row_half_mirror row_mask:0xf bank_mask:0xf bound_ctrl:1
	s_and_saveexec_b64 s[20:21], s[14:15]
	ds_write_b64 v153, v[28:29] offset:51456
	s_or_b64 exec, exec, s[20:21]
	s_waitcnt lgkmcnt(1)
	v_pk_mul_f32 v[66:67], v[46:47], v[42:43] op_sel_hi:[0,1]
	v_pk_fma_f32 v[66:67], v[44:45], v[2:3], v[66:67] op_sel_hi:[0,1,1]
	v_pk_mul_f32 v[46:47], v[46:47], v[64:65] op_sel:[1,0]
	v_pk_fma_f32 v[44:45], v[44:45], v[40:41], v[46:47] op_sel:[1,0,0]
	s_waitcnt lgkmcnt(0)
	v_pk_fma_f32 v[46:47], v[36:37], v[62:63], v[66:67] op_sel_hi:[0,1,1]
	v_pk_fma_f32 v[36:37], v[36:37], v[60:61], v[44:45] op_sel:[1,0,0]
	v_pk_fma_f32 v[44:45], v[38:39], v[72:73], v[46:47] op_sel_hi:[0,1,1]
	v_pk_fma_f32 v[36:37], v[38:39], v[74:75], v[36:37] op_sel:[1,0,0]
	v_pk_add_f32 v[36:37], v[44:45], v[36:37]
	ds_read_b128 v[208:211], v152 offset:6912
	ds_read_b128 v[212:215], v152 offset:6928
	ds_read_b128 v[216:219], v152 offset:11008
	ds_read_b128 v[220:223], v152 offset:11024
	ds_read_b128 v[224:227], v152 offset:15104
	ds_read_b128 v[228:231], v152 offset:15120
	ds_read_b128 v[232:235], v152 offset:19200
	ds_read_b128 v[236:239], v152 offset:19216
	ds_read_b64 v[240:241], v1 offset:23296
	ds_read_b128 v[32:35], v151 offset:2816
	ds_read_b128 v[28:31], v151 offset:2832
	v_add_f32_dpp v36, v36, v36 quad_perm:[1,0,3,2] row_mask:0xf bank_mask:0xf bound_ctrl:1
	v_add_f32_dpp v37, v37, v37 quad_perm:[1,0,3,2] row_mask:0xf bank_mask:0xf bound_ctrl:1
	s_nop 0
	v_add_f32_dpp v36, v36, v36 quad_perm:[2,3,0,1] row_mask:0xf bank_mask:0xf bound_ctrl:1
	v_add_f32_dpp v37, v37, v37 quad_perm:[2,3,0,1] row_mask:0xf bank_mask:0xf bound_ctrl:1
	s_nop 0
	v_add_f32_dpp v36, v36, v36 row_half_mirror row_mask:0xf bank_mask:0xf bound_ctrl:1
	v_add_f32_dpp v37, v37, v37 row_half_mirror row_mask:0xf bank_mask:0xf bound_ctrl:1
	s_nop 0
	v_pk_mul_f32 v[38:39], v[108:109], v[36:37] op_sel_hi:[0,1]
	v_pk_fma_f32 v[38:39], v[116:117], v[132:133], v[38:39] op_sel_hi:[0,1,1] neg_lo:[0,0,1] neg_hi:[0,0,1]
	v_pk_fma_f32 v[70:71], v[2:3], v[100:101], v[38:39] op_sel_hi:[1,0,1]
	v_pk_mul_f32 v[2:3], v[108:109], v[36:37] op_sel:[1,0]
	s_nop 0
	v_pk_fma_f32 v[2:3], v[116:117], v[132:133], v[2:3] op_sel:[1,0,0] neg_lo:[0,0,1] neg_hi:[0,0,1]
	s_nop 0
	v_pk_fma_f32 v[68:69], v[40:41], v[100:101], v[2:3] op_sel:[0,1,0]
	v_pk_mul_f32 v[40:41], v[110:111], v[36:37] op_sel_hi:[0,1]
	v_pk_fma_f32 v[40:41], v[118:119], v[132:133], v[40:41] op_sel_hi:[0,1,1] neg_lo:[0,0,1] neg_hi:[0,0,1]
	v_pk_fma_f32 v[66:67], v[42:43], v[102:103], v[40:41] op_sel_hi:[1,0,1]
	v_pk_mul_f32 v[42:43], v[110:111], v[36:37] op_sel:[1,0]
	v_pk_fma_f32 v[42:43], v[118:119], v[132:133], v[42:43] op_sel:[1,0,0] neg_lo:[0,0,1] neg_hi:[0,0,1]
	v_pk_fma_f32 v[38:39], v[124:125], v[68:69], 0 op_sel:[1,0,0] op_sel_hi:[1,1,0]
	v_pk_fma_f32 v[64:65], v[64:65], v[102:103], v[42:43] op_sel:[0,1,0]
	v_pk_fma_f32 v[38:39], v[126:127], v[64:65], v[38:39] op_sel:[1,0,0]
	v_pk_mul_f32 v[40:41], v[112:113], v[36:37] op_sel_hi:[0,1]
	v_pk_fma_f32 v[40:41], v[120:121], v[132:133], v[40:41] op_sel_hi:[0,1,1] neg_lo:[0,0,1] neg_hi:[0,0,1]
	v_pk_fma_f32 v[62:63], v[62:63], v[104:105], v[40:41] op_sel_hi:[1,0,1]
	v_pk_mul_f32 v[40:41], v[112:113], v[36:37] op_sel:[1,0]
	v_mov_b32_e32 v42, v115
	v_pk_fma_f32 v[40:41], v[120:121], v[132:133], v[40:41] op_sel:[1,0,0] neg_lo:[0,0,1] neg_hi:[0,0,1]
	v_pk_fma_f32 v[2:3], v[124:125], v[70:71], 0 op_sel_hi:[0,1,0]
	v_pk_fma_f32 v[60:61], v[60:61], v[104:105], v[40:41] op_sel:[0,1,0]
	v_pk_mul_f32 v[40:41], v[114:115], v[36:37] op_sel_hi:[0,1]
	v_pk_fma_f32 v[40:41], v[122:123], v[132:133], v[40:41] op_sel_hi:[0,1,1] neg_lo:[0,0,1] neg_hi:[0,0,1]
	v_pk_mul_f32 v[36:37], v[42:43], v[36:37] op_sel_hi:[0,1]
	v_pk_fma_f32 v[2:3], v[126:127], v[66:67], v[2:3] op_sel_hi:[0,1,1]
	v_pk_fma_f32 v[46:47], v[72:73], v[106:107], v[40:41] op_sel_hi:[1,0,1]
	v_mov_b32_e32 v40, v107
	v_pk_fma_f32 v[36:37], v[122:123], v[132:133], v[36:37] op_sel:[1,0,0] neg_lo:[0,0,1] neg_hi:[0,0,1]
	v_pk_fma_f32 v[2:3], v[128:129], v[62:63], v[2:3] op_sel_hi:[0,1,1]
	v_pk_fma_f32 v[38:39], v[128:129], v[60:61], v[38:39] op_sel:[1,0,0]
	v_pk_fma_f32 v[44:45], v[74:75], v[40:41], v[36:37] op_sel_hi:[1,0,1]
	v_pk_fma_f32 v[2:3], v[130:131], v[46:47], v[2:3] op_sel_hi:[0,1,1]
	v_pk_fma_f32 v[36:37], v[130:131], v[44:45], v[38:39] op_sel:[1,0,0]
	v_pk_add_f32 v[2:3], v[2:3], v[36:37]
	s_nop 1
	v_add_f32_dpp v2, v2, v2 quad_perm:[1,0,3,2] row_mask:0xf bank_mask:0xf bound_ctrl:1
	v_add_f32_dpp v3, v3, v3 quad_perm:[1,0,3,2] row_mask:0xf bank_mask:0xf bound_ctrl:1
	s_nop 0
	v_add_f32_dpp v2, v2, v2 quad_perm:[2,3,0,1] row_mask:0xf bank_mask:0xf bound_ctrl:1
	v_add_f32_dpp v3, v3, v3 quad_perm:[2,3,0,1] row_mask:0xf bank_mask:0xf bound_ctrl:1
	s_nop 0
	v_add_f32_dpp v2, v2, v2 row_half_mirror row_mask:0xf bank_mask:0xf bound_ctrl:1
	v_add_f32_dpp v3, v3, v3 row_half_mirror row_mask:0xf bank_mask:0xf bound_ctrl:1
	s_and_saveexec_b64 s[20:21], s[14:15]
	ds_write_b64 v153, v[2:3] offset:51712
	s_or_b64 exec, exec, s[20:21]

.LBB0_635:
	s_andn2_saveexec_b64 s[0:1], s[0:1]
	s_cbranch_execz .LBB0_576
	v_pk_mul_f32 v[2:3], v[66:67], v[34:35] op_sel_hi:[1,0]
	v_pk_fma_f32 v[2:3], v[70:71], v[32:33], v[2:3] op_sel_hi:[1,0,1]
	v_pk_mul_f32 v[34:35], v[64:65], v[34:35] op_sel:[0,1]
	v_pk_fma_f32 v[2:3], v[62:63], v[28:29], v[2:3] op_sel_hi:[1,0,1]
	v_pk_fma_f32 v[32:33], v[68:69], v[32:33], v[34:35] op_sel:[0,1,0]
	v_pk_fma_f32 v[2:3], v[46:47], v[30:31], v[2:3] op_sel_hi:[1,0,1]
	v_pk_fma_f32 v[28:29], v[60:61], v[28:29], v[32:33] op_sel:[0,1,0]
	v_pk_fma_f32 v[28:29], v[44:45], v[30:31], v[28:29] op_sel:[0,1,0]
	s_and_b32 s20, s25, 1
	v_pk_add_f32 v[2:3], v[2:3], v[28:29]
	s_mul_i32 s21, s20, 0x6000
	s_add_i32 s21, s21, 0
	v_add_f32_dpp v2, v2, v2 quad_perm:[1,0,3,2] row_mask:0xf bank_mask:0xf bound_ctrl:1
	v_add_f32_dpp v3, v3, v3 quad_perm:[1,0,3,2] row_mask:0xf bank_mask:0xf bound_ctrl:1
	s_lshl_b32 s22, s20, 12
	s_nop 0
	s_cmp_eq_u32 s20, 1
	v_lshl_add_u32 v1, v97, 2, s21
	v_add_f32_dpp v2, v2, v2 quad_perm:[2,3,0,1] row_mask:0xf bank_mask:0xf bound_ctrl:1
	v_add_f32_dpp v3, v3, v3 quad_perm:[2,3,0,1] row_mask:0xf bank_mask:0xf bound_ctrl:1
	s_cselect_b32 s20, 0x6000, 0
	s_nop 0
	v_lshl_add_u32 v73, v98, 2, s21
	v_add_u32_e32 v74, s20, v143
	ds_read_b128 v[100:103], v1 offset:7168
	ds_read_b128 v[104:107], v1 offset:7184
	ds_read_b128 v[108:111], v1 offset:11264
	ds_read_b128 v[112:115], v1 offset:11280
	ds_read_b128 v[116:119], v1 offset:15360
	ds_read_b128 v[120:123], v1 offset:15376
	ds_read_b128 v[124:127], v1 offset:19456
	ds_read_b128 v[128:131], v1 offset:19472
	ds_read_b64 v[132:133], v73 offset:23552
	ds_read_b128 v[40:43], v74 offset:3072
	ds_read_b128 v[36:39], v74 offset:3088
	v_add_f32_dpp v28, v2, v2 row_half_mirror row_mask:0xf bank_mask:0xf bound_ctrl:1
	v_add_f32_dpp v29, v3, v3 row_half_mirror row_mask:0xf bank_mask:0xf bound_ctrl:1
	v_pk_mul_f32 v[2:3], v[216:217], v[28:29] op_sel_hi:[0,1]
	v_pk_fma_f32 v[2:3], v[224:225], v[240:241], v[2:3] op_sel_hi:[0,1,1] neg_lo:[0,0,1] neg_hi:[0,0,1]
	v_pk_fma_f32 v[2:3], v[70:71], v[208:209], v[2:3] op_sel_hi:[1,0,1]
	v_pk_mul_f32 v[30:31], v[216:217], v[28:29] op_sel:[1,0]
	v_pk_mul_f32 v[34:35], v[218:219], v[28:29] op_sel_hi:[0,1]
	v_pk_fma_f32 v[30:31], v[224:225], v[240:241], v[30:31] op_sel:[1,0,0] neg_lo:[0,0,1] neg_hi:[0,0,1]
	v_pk_fma_f32 v[34:35], v[226:227], v[240:241], v[34:35] op_sel_hi:[0,1,1] neg_lo:[0,0,1] neg_hi:[0,0,1]
	v_pk_mul_f32 v[70:71], v[218:219], v[28:29] op_sel:[1,0]
	v_pk_fma_f32 v[68:69], v[68:69], v[208:209], v[30:31] op_sel:[0,1,0]
	v_pk_fma_f32 v[66:67], v[66:67], v[210:211], v[34:35] op_sel_hi:[1,0,1]
	v_pk_fma_f32 v[70:71], v[226:227], v[240:241], v[70:71] op_sel:[1,0,0] neg_lo:[0,0,1] neg_hi:[0,0,1]
	v_pk_fma_f32 v[32:33], v[232:233], v[68:69], 0 op_sel:[1,0,0] op_sel_hi:[1,1,0]
	v_pk_fma_f32 v[64:65], v[64:65], v[210:211], v[70:71] op_sel:[0,1,0]
	v_pk_fma_f32 v[32:33], v[234:235], v[64:65], v[32:33] op_sel:[1,0,0]
	v_pk_mul_f32 v[34:35], v[220:221], v[28:29] op_sel_hi:[0,1]
	v_pk_fma_f32 v[34:35], v[228:229], v[240:241], v[34:35] op_sel_hi:[0,1,1] neg_lo:[0,0,1] neg_hi:[0,0,1]
	v_pk_fma_f32 v[62:63], v[62:63], v[212:213], v[34:35] op_sel_hi:[1,0,1]
	v_pk_mul_f32 v[34:35], v[220:221], v[28:29] op_sel:[1,0]
	v_pk_fma_f32 v[30:31], v[232:233], v[2:3], 0 op_sel_hi:[0,1,0]
	v_pk_fma_f32 v[34:35], v[228:229], v[240:241], v[34:35] op_sel:[1,0,0] neg_lo:[0,0,1] neg_hi:[0,0,1]
	v_pk_fma_f32 v[60:61], v[60:61], v[212:213], v[34:35] op_sel:[0,1,0]
	v_pk_mul_f32 v[34:35], v[222:223], v[28:29] op_sel_hi:[0,1]
	v_pk_fma_f32 v[30:31], v[234:235], v[66:67], v[30:31] op_sel_hi:[0,1,1]
	v_pk_fma_f32 v[34:35], v[230:231], v[240:241], v[34:35] op_sel_hi:[0,1,1] neg_lo:[0,0,1] neg_hi:[0,0,1]
	v_pk_mul_f32 v[28:29], v[222:223], v[28:29] op_sel:[1,0]
	v_pk_fma_f32 v[30:31], v[236:237], v[62:63], v[30:31] op_sel_hi:[0,1,1]
	v_pk_fma_f32 v[46:47], v[46:47], v[214:215], v[34:35] op_sel_hi:[1,0,1]
	v_pk_fma_f32 v[28:29], v[230:231], v[240:241], v[28:29] op_sel:[1,0,0] neg_lo:[0,0,1] neg_hi:[0,0,1]
	v_pk_fma_f32 v[32:33], v[236:237], v[60:61], v[32:33] op_sel:[1,0,0]
	v_pk_fma_f32 v[44:45], v[44:45], v[214:215], v[28:29] op_sel:[0,1,0]
	v_pk_fma_f32 v[28:29], v[238:239], v[46:47], v[30:31] op_sel_hi:[0,1,1]
	v_pk_fma_f32 v[30:31], v[238:239], v[44:45], v[32:33] op_sel:[1,0,0]
	v_pk_add_f32 v[28:29], v[28:29], v[30:31]
	v_add_u32_e32 v72, s22, v99
	s_nop 0
	v_add_f32_dpp v28, v28, v28 quad_perm:[1,0,3,2] row_mask:0xf bank_mask:0xf bound_ctrl:1
	v_add_f32_dpp v29, v29, v29 quad_perm:[1,0,3,2] row_mask:0xf bank_mask:0xf bound_ctrl:1
	s_nop 0
	v_add_f32_dpp v28, v28, v28 quad_perm:[2,3,0,1] row_mask:0xf bank_mask:0xf bound_ctrl:1
	v_add_f32_dpp v29, v29, v29 quad_perm:[2,3,0,1] row_mask:0xf bank_mask:0xf bound_ctrl:1
	s_nop 0
	v_add_f32_dpp v28, v28, v28 row_half_mirror row_mask:0xf bank_mask:0xf bound_ctrl:1
	v_add_f32_dpp v29, v29, v29 row_half_mirror row_mask:0xf bank_mask:0xf bound_ctrl:1
	s_and_saveexec_b64 s[20:21], s[14:15]
	ds_write_b64 v72, v[28:29] offset:51968
	s_or_b64 exec, exec, s[20:21]
	s_waitcnt lgkmcnt(1)
	v_pk_mul_f32 v[160:161], v[42:43], v[66:67] op_sel_hi:[0,1]
	v_pk_fma_f32 v[160:161], v[40:41], v[2:3], v[160:161] op_sel_hi:[0,1,1]
	v_pk_mul_f32 v[42:43], v[42:43], v[64:65] op_sel:[1,0]
	v_pk_fma_f32 v[40:41], v[40:41], v[68:69], v[42:43] op_sel:[1,0,0]
	s_waitcnt lgkmcnt(0)
	v_pk_fma_f32 v[42:43], v[36:37], v[62:63], v[160:161] op_sel_hi:[0,1,1]
	v_pk_fma_f32 v[36:37], v[36:37], v[60:61], v[40:41] op_sel:[1,0,0]
	v_pk_fma_f32 v[40:41], v[38:39], v[46:47], v[42:43] op_sel_hi:[0,1,1]
	v_pk_fma_f32 v[36:37], v[38:39], v[44:45], v[36:37] op_sel:[1,0,0]
	v_pk_add_f32 v[36:37], v[40:41], v[36:37]
	ds_read_b128 v[208:211], v1 offset:7424
	ds_read_b128 v[212:215], v1 offset:7440
	ds_read_b128 v[216:219], v1 offset:11520
	ds_read_b128 v[220:223], v1 offset:11536
	ds_read_b128 v[224:227], v1 offset:15616
	ds_read_b128 v[228:231], v1 offset:15632
	ds_read_b128 v[232:235], v1 offset:19712
	ds_read_b128 v[236:239], v1 offset:19728
	ds_read_b64 v[240:241], v73 offset:23808
	ds_read_b128 v[32:35], v74 offset:3328
	ds_read_b128 v[28:31], v74 offset:3344
	v_add_f32_dpp v36, v36, v36 quad_perm:[1,0,3,2] row_mask:0xf bank_mask:0xf bound_ctrl:1
	v_add_f32_dpp v37, v37, v37 quad_perm:[1,0,3,2] row_mask:0xf bank_mask:0xf bound_ctrl:1
	s_nop 0
	v_add_f32_dpp v36, v36, v36 quad_perm:[2,3,0,1] row_mask:0xf bank_mask:0xf bound_ctrl:1
	v_add_f32_dpp v37, v37, v37 quad_perm:[2,3,0,1] row_mask:0xf bank_mask:0xf bound_ctrl:1
	s_nop 0
	v_add_f32_dpp v36, v36, v36 row_half_mirror row_mask:0xf bank_mask:0xf bound_ctrl:1
	v_add_f32_dpp v37, v37, v37 row_half_mirror row_mask:0xf bank_mask:0xf bound_ctrl:1
	v_pk_mul_f32 v[38:39], v[108:109], v[36:37] op_sel_hi:[0,1]
	v_pk_fma_f32 v[38:39], v[116:117], v[132:133], v[38:39] op_sel_hi:[0,1,1] neg_lo:[0,0,1] neg_hi:[0,0,1]
	v_pk_fma_f32 v[2:3], v[2:3], v[100:101], v[38:39] op_sel_hi:[1,0,1]
	v_pk_mul_f32 v[38:39], v[108:109], v[36:37] op_sel:[1,0]
	v_pk_mul_f32 v[42:43], v[110:111], v[36:37] op_sel_hi:[0,1]
	v_pk_fma_f32 v[38:39], v[116:117], v[132:133], v[38:39] op_sel:[1,0,0] neg_lo:[0,0,1] neg_hi:[0,0,1]
	v_pk_fma_f32 v[42:43], v[118:119], v[132:133], v[42:43] op_sel_hi:[0,1,1] neg_lo:[0,0,1] neg_hi:[0,0,1]
	v_pk_fma_f32 v[68:69], v[68:69], v[100:101], v[38:39] op_sel:[0,1,0]
	v_pk_fma_f32 v[66:67], v[66:67], v[102:103], v[42:43] op_sel_hi:[1,0,1]
	v_pk_mul_f32 v[152:153], v[110:111], v[36:37] op_sel:[1,0]
	v_pk_fma_f32 v[152:153], v[118:119], v[132:133], v[152:153] op_sel:[1,0,0] neg_lo:[0,0,1] neg_hi:[0,0,1]
	v_pk_fma_f32 v[40:41], v[124:125], v[68:69], 0 op_sel:[1,0,0] op_sel_hi:[1,1,0]
	v_pk_fma_f32 v[64:65], v[64:65], v[102:103], v[152:153] op_sel:[0,1,0]
	v_pk_fma_f32 v[40:41], v[126:127], v[64:65], v[40:41] op_sel:[1,0,0]
	v_pk_mul_f32 v[42:43], v[112:113], v[36:37] op_sel_hi:[0,1]
	v_pk_fma_f32 v[42:43], v[120:121], v[132:133], v[42:43] op_sel_hi:[0,1,1] neg_lo:[0,0,1] neg_hi:[0,0,1]
	v_pk_fma_f32 v[62:63], v[62:63], v[104:105], v[42:43] op_sel_hi:[1,0,1]
	v_pk_mul_f32 v[42:43], v[112:113], v[36:37] op_sel:[1,0]
	v_pk_fma_f32 v[38:39], v[124:125], v[2:3], 0 op_sel_hi:[0,1,0]
	v_pk_fma_f32 v[42:43], v[120:121], v[132:133], v[42:43] op_sel:[1,0,0] neg_lo:[0,0,1] neg_hi:[0,0,1]
	v_pk_fma_f32 v[60:61], v[60:61], v[104:105], v[42:43] op_sel:[0,1,0]
	v_pk_mul_f32 v[42:43], v[114:115], v[36:37] op_sel_hi:[0,1]
	v_pk_fma_f32 v[38:39], v[126:127], v[66:67], v[38:39] op_sel_hi:[0,1,1]
	v_pk_fma_f32 v[42:43], v[122:123], v[132:133], v[42:43] op_sel_hi:[0,1,1] neg_lo:[0,0,1] neg_hi:[0,0,1]
	v_pk_mul_f32 v[36:37], v[114:115], v[36:37] op_sel:[1,0]
	v_pk_fma_f32 v[38:39], v[128:129], v[62:63], v[38:39] op_sel_hi:[0,1,1]
	v_pk_fma_f32 v[46:47], v[46:47], v[106:107], v[42:43] op_sel_hi:[1,0,1]
	v_pk_fma_f32 v[36:37], v[122:123], v[132:133], v[36:37] op_sel:[1,0,0] neg_lo:[0,0,1] neg_hi:[0,0,1]
	v_pk_fma_f32 v[40:41], v[128:129], v[60:61], v[40:41] op_sel:[1,0,0]
	v_pk_fma_f32 v[44:45], v[44:45], v[106:107], v[36:37] op_sel:[0,1,0]
	v_pk_fma_f32 v[36:37], v[130:131], v[46:47], v[38:39] op_sel_hi:[0,1,1]
	v_pk_fma_f32 v[38:39], v[130:131], v[44:45], v[40:41] op_sel:[1,0,0]
	v_pk_add_f32 v[36:37], v[36:37], v[38:39]
	s_nop 1
	v_add_f32_dpp v36, v36, v36 quad_perm:[1,0,3,2] row_mask:0xf bank_mask:0xf bound_ctrl:1
	v_add_f32_dpp v37, v37, v37 quad_perm:[1,0,3,2] row_mask:0xf bank_mask:0xf bound_ctrl:1
	s_nop 0
	v_add_f32_dpp v36, v36, v36 quad_perm:[2,3,0,1] row_mask:0xf bank_mask:0xf bound_ctrl:1
	v_add_f32_dpp v37, v37, v37 quad_perm:[2,3,0,1] row_mask:0xf bank_mask:0xf bound_ctrl:1
	s_nop 0
	v_add_f32_dpp v36, v36, v36 row_half_mirror row_mask:0xf bank_mask:0xf bound_ctrl:1
	v_add_f32_dpp v37, v37, v37 row_half_mirror row_mask:0xf bank_mask:0xf bound_ctrl:1
	s_and_saveexec_b64 s[20:21], s[14:15]
	ds_write_b64 v72, v[36:37] offset:52224
	s_or_b64 exec, exec, s[20:21]
	s_waitcnt lgkmcnt(1)
	v_pk_mul_f32 v[160:161], v[34:35], v[66:67] op_sel_hi:[0,1]
	v_pk_fma_f32 v[160:161], v[32:33], v[2:3], v[160:161] op_sel_hi:[0,1,1]
	v_pk_mul_f32 v[34:35], v[34:35], v[64:65] op_sel:[1,0]
	v_pk_fma_f32 v[32:33], v[32:33], v[68:69], v[34:35] op_sel:[1,0,0]
	s_waitcnt lgkmcnt(0)
	v_pk_fma_f32 v[34:35], v[28:29], v[62:63], v[160:161] op_sel_hi:[0,1,1]
	v_pk_fma_f32 v[28:29], v[28:29], v[60:61], v[32:33] op_sel:[1,0,0]
	v_pk_fma_f32 v[32:33], v[30:31], v[46:47], v[34:35] op_sel_hi:[0,1,1]
	v_pk_fma_f32 v[28:29], v[30:31], v[44:45], v[28:29] op_sel:[1,0,0]
	v_pk_add_f32 v[28:29], v[32:33], v[28:29]
	ds_read_b128 v[40:43], v74 offset:3584
	ds_read_b128 v[36:39], v74 offset:3600
	v_add_f32_dpp v28, v28, v28 quad_perm:[1,0,3,2] row_mask:0xf bank_mask:0xf bound_ctrl:1
	v_add_f32_dpp v29, v29, v29 quad_perm:[1,0,3,2] row_mask:0xf bank_mask:0xf bound_ctrl:1
	s_nop 0
	v_add_f32_dpp v28, v28, v28 quad_perm:[2,3,0,1] row_mask:0xf bank_mask:0xf bound_ctrl:1
	v_add_f32_dpp v29, v29, v29 quad_perm:[2,3,0,1] row_mask:0xf bank_mask:0xf bound_ctrl:1
	s_nop 0
	v_add_f32_dpp v28, v28, v28 row_half_mirror row_mask:0xf bank_mask:0xf bound_ctrl:1
	v_add_f32_dpp v29, v29, v29 row_half_mirror row_mask:0xf bank_mask:0xf bound_ctrl:1
	v_pk_mul_f32 v[30:31], v[216:217], v[28:29] op_sel_hi:[0,1]
	v_pk_fma_f32 v[30:31], v[224:225], v[240:241], v[30:31] op_sel_hi:[0,1,1] neg_lo:[0,0,1] neg_hi:[0,0,1]
	v_pk_fma_f32 v[2:3], v[2:3], v[208:209], v[30:31] op_sel_hi:[1,0,1]
	v_pk_mul_f32 v[30:31], v[216:217], v[28:29] op_sel:[1,0]
	v_pk_mul_f32 v[34:35], v[218:219], v[28:29] op_sel_hi:[0,1]
	v_pk_fma_f32 v[30:31], v[224:225], v[240:241], v[30:31] op_sel:[1,0,0] neg_lo:[0,0,1] neg_hi:[0,0,1]
	v_pk_fma_f32 v[34:35], v[226:227], v[240:241], v[34:35] op_sel_hi:[0,1,1] neg_lo:[0,0,1] neg_hi:[0,0,1]
	v_pk_fma_f32 v[68:69], v[68:69], v[208:209], v[30:31] op_sel:[0,1,0]
	v_pk_fma_f32 v[66:67], v[66:67], v[210:211], v[34:35] op_sel_hi:[1,0,1]
	v_pk_mul_f32 v[152:153], v[218:219], v[28:29] op_sel:[1,0]
	v_pk_fma_f32 v[152:153], v[226:227], v[240:241], v[152:153] op_sel:[1,0,0] neg_lo:[0,0,1] neg_hi:[0,0,1]
	v_pk_fma_f32 v[32:33], v[232:233], v[68:69], 0 op_sel:[1,0,0] op_sel_hi:[1,1,0]
	v_pk_fma_f32 v[64:65], v[64:65], v[210:211], v[152:153] op_sel:[0,1,0]
	v_pk_fma_f32 v[32:33], v[234:235], v[64:65], v[32:33] op_sel:[1,0,0]
	v_pk_mul_f32 v[34:35], v[220:221], v[28:29] op_sel_hi:[0,1]
	v_pk_fma_f32 v[34:35], v[228:229], v[240:241], v[34:35] op_sel_hi:[0,1,1] neg_lo:[0,0,1] neg_hi:[0,0,1]
	v_pk_fma_f32 v[62:63], v[62:63], v[212:213], v[34:35] op_sel_hi:[1,0,1]
	v_pk_mul_f32 v[34:35], v[220:221], v[28:29] op_sel:[1,0]
	v_pk_fma_f32 v[30:31], v[232:233], v[2:3], 0 op_sel_hi:[0,1,0]
	v_pk_fma_f32 v[34:35], v[228:229], v[240:241], v[34:35] op_sel:[1,0,0] neg_lo:[0,0,1] neg_hi:[0,0,1]
	v_pk_fma_f32 v[60:61], v[60:61], v[212:213], v[34:35] op_sel:[0,1,0]
	v_pk_mul_f32 v[34:35], v[222:223], v[28:29] op_sel_hi:[0,1]
	v_pk_fma_f32 v[30:31], v[234:235], v[66:67], v[30:31] op_sel_hi:[0,1,1]
	v_pk_fma_f32 v[34:35], v[230:231], v[240:241], v[34:35] op_sel_hi:[0,1,1] neg_lo:[0,0,1] neg_hi:[0,0,1]
	v_pk_mul_f32 v[28:29], v[222:223], v[28:29] op_sel:[1,0]
	v_pk_fma_f32 v[30:31], v[236:237], v[62:63], v[30:31] op_sel_hi:[0,1,1]
	v_pk_fma_f32 v[46:47], v[46:47], v[214:215], v[34:35] op_sel_hi:[1,0,1]
	v_pk_fma_f32 v[28:29], v[230:231], v[240:241], v[28:29] op_sel:[1,0,0] neg_lo:[0,0,1] neg_hi:[0,0,1]
	v_pk_fma_f32 v[32:33], v[236:237], v[60:61], v[32:33] op_sel:[1,0,0]
	v_pk_fma_f32 v[44:45], v[44:45], v[214:215], v[28:29] op_sel:[0,1,0]
	v_pk_fma_f32 v[28:29], v[238:239], v[46:47], v[30:31] op_sel_hi:[0,1,1]
	v_pk_fma_f32 v[30:31], v[238:239], v[44:45], v[32:33] op_sel:[1,0,0]
	v_pk_add_f32 v[28:29], v[28:29], v[30:31]
	s_nop 1
	v_add_f32_dpp v28, v28, v28 quad_perm:[1,0,3,2] row_mask:0xf bank_mask:0xf bound_ctrl:1
	v_add_f32_dpp v29, v29, v29 quad_perm:[1,0,3,2] row_mask:0xf bank_mask:0xf bound_ctrl:1
	s_nop 0
	v_add_f32_dpp v28, v28, v28 quad_perm:[2,3,0,1] row_mask:0xf bank_mask:0xf bound_ctrl:1
	v_add_f32_dpp v29, v29, v29 quad_perm:[2,3,0,1] row_mask:0xf bank_mask:0xf bound_ctrl:1
	s_nop 0
	v_add_f32_dpp v28, v28, v28 row_half_mirror row_mask:0xf bank_mask:0xf bound_ctrl:1
	v_add_f32_dpp v29, v29, v29 row_half_mirror row_mask:0xf bank_mask:0xf bound_ctrl:1
	s_and_saveexec_b64 s[20:21], s[14:15]
	ds_write_b64 v72, v[28:29] offset:52480
	s_or_b64 exec, exec, s[20:21]
	ds_read_b128 v[152:155], v1 offset:7680
	ds_read_b128 v[156:159], v1 offset:7696
	ds_read_b128 v[166:169], v1 offset:11776
	ds_read_b128 v[170:173], v1 offset:11792
	ds_read_b128 v[174:177], v1 offset:15872
	ds_read_b128 v[178:181], v1 offset:15888
	ds_read_b128 v[198:201], v1 offset:19968
	ds_read_b128 v[202:205], v1 offset:19984
	ds_read_b64 v[70:71], v73 offset:24064
	ds_read_b128 v[32:35], v74 offset:3840
	ds_read_b128 v[28:31], v74 offset:3856
	s_waitcnt lgkmcnt(12)
	v_pk_mul_f32 v[74:75], v[42:43], v[66:67] op_sel_hi:[0,1]
	v_pk_fma_f32 v[74:75], v[40:41], v[2:3], v[74:75] op_sel_hi:[0,1,1]
	v_pk_mul_f32 v[42:43], v[42:43], v[64:65] op_sel:[1,0]
	v_pk_fma_f32 v[40:41], v[40:41], v[68:69], v[42:43] op_sel:[1,0,0]
	s_waitcnt lgkmcnt(11)
	v_pk_fma_f32 v[42:43], v[36:37], v[62:63], v[74:75] op_sel_hi:[0,1,1]
	v_pk_fma_f32 v[36:37], v[36:37], v[60:61], v[40:41] op_sel:[1,0,0]
	v_pk_fma_f32 v[40:41], v[38:39], v[46:47], v[42:43] op_sel_hi:[0,1,1]
	v_pk_fma_f32 v[36:37], v[38:39], v[44:45], v[36:37] op_sel:[1,0,0]
	v_pk_add_f32 v[36:37], v[40:41], v[36:37]
	s_waitcnt lgkmcnt(10)
	s_nop 0
	v_add_f32_dpp v36, v36, v36 quad_perm:[1,0,3,2] row_mask:0xf bank_mask:0xf bound_ctrl:1
	v_add_f32_dpp v37, v37, v37 quad_perm:[1,0,3,2] row_mask:0xf bank_mask:0xf bound_ctrl:1
	s_nop 0
	v_add_f32_dpp v36, v36, v36 quad_perm:[2,3,0,1] row_mask:0xf bank_mask:0xf bound_ctrl:1
	v_add_f32_dpp v37, v37, v37 quad_perm:[2,3,0,1] row_mask:0xf bank_mask:0xf bound_ctrl:1
	s_nop 0
	v_add_f32_dpp v74, v36, v36 row_half_mirror row_mask:0xf bank_mask:0xf bound_ctrl:1
	v_add_f32_dpp v75, v37, v37 row_half_mirror row_mask:0xf bank_mask:0xf bound_ctrl:1
	s_waitcnt lgkmcnt(8)
	v_pk_mul_f32 v[36:37], v[166:167], v[74:75] op_sel_hi:[0,1]
	s_waitcnt lgkmcnt(2)
	v_pk_fma_f32 v[36:37], v[174:175], v[70:71], v[36:37] op_sel_hi:[0,1,1] neg_lo:[0,0,1] neg_hi:[0,0,1]
	v_pk_mul_f32 v[38:39], v[168:169], v[74:75] op_sel_hi:[0,1]
	v_pk_fma_f32 v[2:3], v[2:3], v[152:153], v[36:37] op_sel_hi:[1,0,1]
	v_pk_mul_f32 v[36:37], v[166:167], v[74:75] op_sel:[1,0]
	v_pk_fma_f32 v[38:39], v[176:177], v[70:71], v[38:39] op_sel_hi:[0,1,1] neg_lo:[0,0,1] neg_hi:[0,0,1]
	v_pk_fma_f32 v[36:37], v[174:175], v[70:71], v[36:37] op_sel:[1,0,0] neg_lo:[0,0,1] neg_hi:[0,0,1]
	v_pk_fma_f32 v[38:39], v[66:67], v[154:155], v[38:39] op_sel_hi:[1,0,1]
	v_pk_fma_f32 v[36:37], v[68:69], v[152:153], v[36:37] op_sel:[0,1,0]
	v_pk_mul_f32 v[66:67], v[168:169], v[74:75] op_sel:[1,0]
	v_pk_fma_f32 v[42:43], v[198:199], v[2:3], 0 op_sel_hi:[0,1,0]
	v_pk_fma_f32 v[66:67], v[176:177], v[70:71], v[66:67] op_sel:[1,0,0] neg_lo:[0,0,1] neg_hi:[0,0,1]
	v_pk_fma_f32 v[68:69], v[198:199], v[36:37], 0 op_sel:[1,0,0] op_sel_hi:[1,1,0]
	v_pk_fma_f32 v[40:41], v[64:65], v[154:155], v[66:67] op_sel:[0,1,0]
	v_pk_fma_f32 v[64:65], v[200:201], v[38:39], v[42:43] op_sel_hi:[0,1,1]
	v_pk_fma_f32 v[66:67], v[200:201], v[40:41], v[68:69] op_sel:[1,0,0]
	v_pk_mul_f32 v[42:43], v[170:171], v[74:75] op_sel_hi:[0,1]
	v_pk_fma_f32 v[42:43], v[178:179], v[70:71], v[42:43] op_sel_hi:[0,1,1] neg_lo:[0,0,1] neg_hi:[0,0,1]
	v_pk_fma_f32 v[42:43], v[62:63], v[156:157], v[42:43] op_sel_hi:[1,0,1]
	v_pk_mul_f32 v[62:63], v[170:171], v[74:75] op_sel:[1,0]
	v_pk_fma_f32 v[62:63], v[178:179], v[70:71], v[62:63] op_sel:[1,0,0] neg_lo:[0,0,1] neg_hi:[0,0,1]
	v_pk_fma_f32 v[60:61], v[60:61], v[156:157], v[62:63] op_sel:[0,1,0]
	v_pk_fma_f32 v[62:63], v[202:203], v[42:43], v[64:65] op_sel_hi:[0,1,1]
	v_pk_fma_f32 v[64:65], v[202:203], v[60:61], v[66:67] op_sel:[1,0,0]
	v_pk_mul_f32 v[66:67], v[172:173], v[74:75] op_sel_hi:[0,1]
	v_pk_fma_f32 v[66:67], v[180:181], v[70:71], v[66:67] op_sel_hi:[0,1,1] neg_lo:[0,0,1] neg_hi:[0,0,1]
	v_pk_mul_f32 v[68:69], v[172:173], v[74:75] op_sel:[1,0]
	v_pk_fma_f32 v[46:47], v[46:47], v[158:159], v[66:67] op_sel_hi:[1,0,1]
	v_pk_fma_f32 v[68:69], v[180:181], v[70:71], v[68:69] op_sel:[1,0,0] neg_lo:[0,0,1] neg_hi:[0,0,1]
	v_pk_fma_f32 v[44:45], v[44:45], v[158:159], v[68:69] op_sel:[0,1,0]
	v_pk_fma_f32 v[62:63], v[204:205], v[46:47], v[62:63] op_sel_hi:[0,1,1]
	v_pk_fma_f32 v[64:65], v[204:205], v[44:45], v[64:65] op_sel:[1,0,0]
	v_pk_add_f32 v[62:63], v[62:63], v[64:65]
	s_nop 1
	v_add_f32_dpp v62, v62, v62 quad_perm:[1,0,3,2] row_mask:0xf bank_mask:0xf bound_ctrl:1
	v_add_f32_dpp v63, v63, v63 quad_perm:[1,0,3,2] row_mask:0xf bank_mask:0xf bound_ctrl:1
	s_nop 0
	v_add_f32_dpp v62, v62, v62 quad_perm:[2,3,0,1] row_mask:0xf bank_mask:0xf bound_ctrl:1
	v_add_f32_dpp v63, v63, v63 quad_perm:[2,3,0,1] row_mask:0xf bank_mask:0xf bound_ctrl:1
	s_nop 0
	v_add_f32_dpp v62, v62, v62 row_half_mirror row_mask:0xf bank_mask:0xf bound_ctrl:1
	v_add_f32_dpp v63, v63, v63 row_half_mirror row_mask:0xf bank_mask:0xf bound_ctrl:1
	s_and_saveexec_b64 s[20:21], s[14:15]
	ds_write_b64 v72, v[62:63] offset:52736
	s_or_b64 exec, exec, s[20:21]
	s_waitcnt lgkmcnt(1)
	v_pk_mul_f32 v[66:67], v[34:35], v[38:39] op_sel_hi:[0,1]
	v_pk_mul_f32 v[68:69], v[34:35], v[40:41] op_sel:[1,0]
	v_pk_fma_f32 v[66:67], v[32:33], v[2:3], v[66:67] op_sel_hi:[0,1,1]
	v_pk_fma_f32 v[68:69], v[32:33], v[36:37], v[68:69] op_sel:[1,0,0]
	s_waitcnt lgkmcnt(0)
	v_pk_fma_f32 v[66:67], v[28:29], v[42:43], v[66:67] op_sel_hi:[0,1,1]
	v_pk_fma_f32 v[68:69], v[28:29], v[60:61], v[68:69] op_sel:[1,0,0]
	v_pk_fma_f32 v[66:67], v[30:31], v[46:47], v[66:67] op_sel_hi:[0,1,1]
	v_pk_fma_f32 v[68:69], v[30:31], v[44:45], v[68:69] op_sel:[1,0,0]
	v_pk_add_f32 v[66:67], v[66:67], v[68:69]
	ds_read_b64 v[74:75], v73 offset:24320
	ds_read_b128 v[152:155], v1 offset:20240
	ds_read_b128 v[156:159], v1 offset:20224
	ds_read_b128 v[166:169], v1 offset:16144
	ds_read_b128 v[62:65], v1 offset:16128
	ds_read_b128 v[170:173], v1 offset:12048
	ds_read_b128 v[174:177], v1 offset:12032
	ds_read_b128 v[178:181], v1 offset:7936
	ds_read_b128 v[198:201], v1 offset:7952
	v_add_f32_dpp v66, v66, v66 quad_perm:[1,0,3,2] row_mask:0xf bank_mask:0xf bound_ctrl:1
	v_add_f32_dpp v67, v67, v67 quad_perm:[1,0,3,2] row_mask:0xf bank_mask:0xf bound_ctrl:1
	s_nop 0
	v_add_f32_dpp v66, v66, v66 quad_perm:[2,3,0,1] row_mask:0xf bank_mask:0xf bound_ctrl:1
	v_add_f32_dpp v67, v67, v67 quad_perm:[2,3,0,1] row_mask:0xf bank_mask:0xf bound_ctrl:1
	s_nop 0
	v_add_f32_dpp v160, v66, v66 row_half_mirror row_mask:0xf bank_mask:0xf bound_ctrl:1
	v_add_f32_dpp v161, v67, v67 row_half_mirror row_mask:0xf bank_mask:0xf bound_ctrl:1
	s_waitcnt lgkmcnt(2)
	v_pk_mul_f32 v[66:67], v[174:175], v[160:161] op_sel_hi:[0,1]
	v_pk_fma_f32 v[66:67], v[74:75], v[62:63], v[66:67] op_sel_hi:[1,0,1] neg_lo:[0,0,1] neg_hi:[0,0,1]
	s_waitcnt lgkmcnt(1)
	v_pk_fma_f32 v[70:71], v[2:3], v[178:179], v[66:67] op_sel_hi:[1,0,1]
	v_pk_mul_f32 v[2:3], v[174:175], v[160:161] op_sel:[1,0]
	s_nop 0
	v_pk_fma_f32 v[2:3], v[74:75], v[62:63], v[2:3] op_sel:[0,1,0] neg_lo:[0,0,1] neg_hi:[0,0,1]
	v_pk_mul_f32 v[62:63], v[176:177], v[160:161] op_sel_hi:[0,1]
	v_pk_fma_f32 v[62:63], v[74:75], v[64:65], v[62:63] op_sel_hi:[1,0,1] neg_lo:[0,0,1] neg_hi:[0,0,1]
	v_pk_fma_f32 v[66:67], v[38:39], v[180:181], v[62:63] op_sel_hi:[1,0,1]
	v_pk_mul_f32 v[62:63], v[176:177], v[160:161] op_sel:[1,0]
	v_pk_fma_f32 v[68:69], v[36:37], v[178:179], v[2:3] op_sel:[0,1,0]
	v_pk_fma_f32 v[62:63], v[74:75], v[64:65], v[62:63] op_sel:[0,1,0] neg_lo:[0,0,1] neg_hi:[0,0,1]
	v_pk_fma_f32 v[36:37], v[156:157], v[68:69], 0 op_sel:[1,0,0] op_sel_hi:[1,1,0]
	v_pk_fma_f32 v[64:65], v[40:41], v[180:181], v[62:63] op_sel:[0,1,0]
	v_pk_fma_f32 v[36:37], v[158:159], v[64:65], v[36:37] op_sel:[1,0,0]
	v_pk_mul_f32 v[38:39], v[170:171], v[160:161] op_sel_hi:[0,1]
	v_pk_fma_f32 v[38:39], v[74:75], v[166:167], v[38:39] op_sel_hi:[1,0,1] neg_lo:[0,0,1] neg_hi:[0,0,1]
	s_waitcnt lgkmcnt(0)
	v_pk_fma_f32 v[62:63], v[42:43], v[198:199], v[38:39] op_sel_hi:[1,0,1]
	v_pk_mul_f32 v[38:39], v[170:171], v[160:161] op_sel:[1,0]
	v_pk_fma_f32 v[2:3], v[156:157], v[70:71], 0 op_sel_hi:[0,1,0]
	v_pk_fma_f32 v[38:39], v[74:75], v[166:167], v[38:39] op_sel:[0,1,0] neg_lo:[0,0,1] neg_hi:[0,0,1]
	v_mov_b32_e32 v42, v169
	v_pk_fma_f32 v[60:61], v[60:61], v[198:199], v[38:39] op_sel:[0,1,0]
	v_pk_mul_f32 v[38:39], v[172:173], v[160:161] op_sel_hi:[0,1]
	v_pk_fma_f32 v[38:39], v[74:75], v[168:169], v[38:39] op_sel_hi:[1,0,1] neg_lo:[0,0,1] neg_hi:[0,0,1]
	v_pk_mul_f32 v[40:41], v[172:173], v[160:161] op_sel:[1,0]
	v_pk_fma_f32 v[2:3], v[158:159], v[66:67], v[2:3] op_sel_hi:[0,1,1]
	v_pk_fma_f32 v[46:47], v[46:47], v[200:201], v[38:39] op_sel_hi:[1,0,1]
	v_pk_fma_f32 v[40:41], v[74:75], v[42:43], v[40:41] op_sel_hi:[1,0,1] neg_lo:[0,0,1] neg_hi:[0,0,1]
	v_pk_fma_f32 v[2:3], v[152:153], v[62:63], v[2:3] op_sel_hi:[0,1,1]
	v_pk_fma_f32 v[36:37], v[152:153], v[60:61], v[36:37] op_sel:[1,0,0]
	v_pk_fma_f32 v[44:45], v[44:45], v[200:201], v[40:41] op_sel:[0,1,0]
	v_mov_b32_e32 v38, v155
	v_pk_fma_f32 v[2:3], v[154:155], v[46:47], v[2:3] op_sel_hi:[0,1,1]
	v_pk_fma_f32 v[36:37], v[38:39], v[44:45], v[36:37] op_sel_hi:[0,1,1]
	v_pk_add_f32 v[2:3], v[2:3], v[36:37]
	s_nop 1
	v_add_f32_dpp v2, v2, v2 quad_perm:[1,0,3,2] row_mask:0xf bank_mask:0xf bound_ctrl:1
	v_add_f32_dpp v3, v3, v3 quad_perm:[1,0,3,2] row_mask:0xf bank_mask:0xf bound_ctrl:1
	s_nop 0
	v_add_f32_dpp v2, v2, v2 quad_perm:[2,3,0,1] row_mask:0xf bank_mask:0xf bound_ctrl:1
	v_add_f32_dpp v3, v3, v3 quad_perm:[2,3,0,1] row_mask:0xf bank_mask:0xf bound_ctrl:1
	s_nop 0
	v_mov_b32_dpp v36, v2 row_half_mirror row_mask:0xf bank_mask:0xf bound_ctrl:1
	v_mov_b32_dpp v37, v3 row_half_mirror row_mask:0xf bank_mask:0xf bound_ctrl:1
	s_and_saveexec_b64 s[20:21], s[14:15]
	s_cbranch_execz .LBB0_575
	v_pk_add_f32 v[2:3], v[2:3], v[36:37]
	ds_write_b64 v72, v[2:3] offset:52992
	s_branch .LBB0_575
